# mLSTM chunk prefetch kept in flight (counted vmcnt), attention finalize gate loads batched (A and C) instead of a load+store round trip per 4 channels
# speedup vs baseline: 1.1011x; 1.0123x over previous
; template <int MX>
; DI RecRaw rec_load(const Params& p, int b, int h, int dir, int T0, int tid) {
;   const bf16_t* P = (const bf16_t*)(p.ws + WS_P);
;   const int tt = tid >> 2, k0 = (tid & 3) * 16;
;   const size_t row = (size_t)b * NTOK + T0 + tt;
;   const bf16_t* rp = P + row * PW;
;   RecRaw w;
;   if (MX == 0) {
;     const int fcol = (dir ? B_FB : B_FF) + h * 64 + k0;
;     w.a0 = *(const uint4*)(rp + fcol); w.a1 = *(const uint4*)(rp + fcol + 8);
;     w.b0 = *(const uint4*)(rp + B_Q + h * 64 + k0); w.b1 = *(const uint4*)(rp + B_Q + h * 64 + k0 + 8);
;     w.c0 = *(const uint4*)(rp + B_I + h * 64 + k0); w.c1 = *(const uint4*)(rp + B_I + h * 64 + k0 + 8);
;     w.ig = 0.f; w.fg = 0.f;
;   } else {
;     w.a0 = *(const uint4*)(rp + D_K + h * 64 + k0); w.a1 = *(const uint4*)(rp + D_K + h * 64 + k0 + 8);
;     w.b0 = *(const uint4*)(rp + D_Q + h * 64 + k0); w.b1 = *(const uint4*)(rp + D_Q + h * 64 + k0 + 8);
;     w.c0 = *(const uint4*)(rp + D_V + h * 64 + k0); w.c1 = *(const uint4*)(rp + D_V + h * 64 + k0 + 8);
;     const float* G = (const float*)(p.ws + WS_GATES) + row * 16;
;     w.ig = G[dir * 4 + h]; w.fg = G[8 + dir * 4 + h];
;   }
;   return w;
; }
; template <int MX, bool OUT>
; DI void rec_chunk(const Params& p, int l, int b, int h, int dir, int T0, unsigned char* smem, f32x4 (&St)[4], float& nst, float& dtot, int tid, const RecRaw& raw) {
;     ...
;       const float ig = raw.ig, fg = raw.fg;
;       const float lfs = (fg < -20.f) ? fg * 1.4426950408889634f : -__log2f(1.f + __expf(-fg));
;       const float ei = __expf(ig) * 0.125f;
.LBB0_438:
	s_cmp_eq_u32 s52, -1
	s_cselect_b32 s34, 3, s53
	s_cselect_b32 s35, 0, s52
	s_and_b64 s[22:23], s[0:1], exec
	s_cselect_b32 s22, s34, s35
	s_lshl_b32 s22, s22, 6
	s_add_i32 s22, s22, s51
	s_ashr_i32 s23, s22, 31
	v_lshl_add_u64 v[86:87], v[50:51], 0, s[22:23]
	v_mov_b64_e32 v[0:1], s[28:29]
	v_mad_u64_u32 v[0:1], s[22:23], v86, s33, v[0:1]
	v_mad_i32_i24 v1, v87, s33, v1
	v_lshl_add_u64 v[0:1], v[0:1], 0, s[2:3]
	v_lshl_add_u64 v[4:5], v[0:1], 0, v[160:161]
	s_mov_b64 s[22:23], 0x1400
	v_lshl_add_u64 v[0:1], v[4:5], 0, s[22:23]
	v_add_co_u32_e32 v6, vcc, s16, v4
	s_mov_b64 s[22:23], 0x1600
	v_lshlrev_b64 v[86:87], 6, v[86:87]
	v_addc_co_u32_e32 v7, vcc, 0, v5, vcc
	v_lshl_add_u64 v[4:5], v[4:5], 0, s[22:23]
	v_lshl_add_u64 v[88:89], s[30:31], 0, v[86:87]
	global_load_dwordx4 v[8:11], v[6:7], off offset:1024
	s_nop 0
	global_load_dwordx4 v[0:3], v[0:1], off offset:16
	s_nop 0
	global_load_dwordx4 v[12:15], v[6:7], off offset:1536
	s_nop 0
	global_load_dwordx4 v[4:7], v[4:5], off offset:16
	s_nop 0
	global_load_dword v86, v[88:89], off
	global_load_dword v87, v[88:89], off offset:32
	s_mov_b32 s22, 0xc1a00000
	s_waitcnt vmcnt(6) lgkmcnt(0)
	v_cmp_ngt_f32_e32 vcc, s22, v53
	s_and_saveexec_b64 s[22:23], vcc
	s_xor_b64 s[22:23], exec, s[22:23]
	s_cbranch_execz .LBB0_504
	v_mul_f32_e32 v53, 0xbfb8aa3b, v53
	v_exp_f32_e32 v53, v53
	s_nop 0
	v_add_f32_e32 v53, 1.0, v53
	v_log_f32_e32 v53, v53
	s_nop 0
	v_xor_b32_e32 v88, 0x80000000, v53
	s_andn2_saveexec_b64 s[22:23], s[22:23]
	s_cbranch_execnz .LBB0_505

; template <int MX>
; DI void rec_summary(const Params& p, int l, int b, int h, int dir, int sc, unsigned char* smem) {
;     ...
; #pragma unroll 1
;   for (int ci = 0; ci < 4; ++ci) {
;     const int c = dir == 0 ? ci : 3 - ci;
;     const int cn = dir == 0 ? (ci < 3 ? ci + 1 : ci) : (ci < 3 ? 2 - ci : 0);
;     const RecRaw nxt = rec_load<MX>(p, b, h, dir, sc * 256 + cn * 64, tid);
;     rec_chunk<MX, false>(p, l, b, h, dir, sc * 256 + c * 64, smem, St, nst, dtot, tid, raw);
;     raw = nxt;
;   }
.LBB0_502:
	s_or_b64 exec, exec, s[22:23]
	s_add_i32 s52, s52, -1
	s_add_i32 s53, s53, 1
	s_cmp_eq_u32 s52, -2
	s_waitcnt vmcnt(0)
	s_barrier
	s_cbranch_scc1 .LBB0_506
	v_mov_b32_e32 v52, v86
	v_mov_b32_e32 v53, v87
	v_mov_b64_e32 v[40:41], v[8:9]
	v_mov_b64_e32 v[42:43], v[10:11]
	v_mov_b64_e32 v[32:33], v[0:1]
	v_mov_b64_e32 v[34:35], v[2:3]
	v_mov_b64_e32 v[44:45], v[12:13]
	v_mov_b64_e32 v[46:47], v[14:15]
	v_mov_b64_e32 v[36:37], v[4:5]
	v_mov_b64_e32 v[38:39], v[6:7]
	s_branch .LBB0_438

; DI size_t kblk(int row, int col, int nrows) { return ((size_t)(col >> 5) * nrows + row) * 32 + (col & 31); }
; DI float bf2f(bf16_t v) { return __uint_as_float(((unsigned)v) << 16); }
; DI unsigned pk2(float a, float b) { hwf32x2 f = {a, b}; hwbf16x2 r = __builtin_convertvector(f, hwbf16x2); return __builtin_bit_cast(unsigned, r); }
; DI float siluf_(float z) { return z / (1.f + __expf(-z)); }
; DI int crow(int reg, int h) { return (reg & 3) + 8 * (reg >> 2) + 4 * h; }
; template <int MODE>
; DI void attn_mfma(const Params& p, int l, int b, int hd, int qb, unsigned char* smem) {
;     ...
;     __syncthreads();
;     if (mp == 0) {
;       const float i0 = 1.f / ltot;
;       float ss = 0.f;
; #pragma unroll
;       for (int vt = 0; vt < 2; ++vt)
; #pragma unroll
;         for (int i = 0; i < 16; ++i) { const float o = O[vt][i] * i0 - sO[ql * 65 + vt * 32 + crow(i, h2)]; O[vt][i] = o; ss += o * o; }
;       ss += __shfl_xor(ss, 32);
;       const float rstd = rsqrtf(ss * (1.f / 64.f) + EPS) * (1.f - lam_init);
; #pragma unroll
;       for (int vt = 0; vt < 2; ++vt)
; #pragma unroll
;         for (int g4 = 0; g4 < 4; ++g4) {
;           const int v0 = vt * 32 + 8 * g4 + 4 * h2;
;           const ushort4 gt = *(const ushort4*)(P + qrow * PW + GATE + hd * 64 + v0);
;           const float4 gg = *(const float4*)(p.diff_g + l * 64 + v0);
;           uint2 o;
;           o.x = pk2(O[vt][4 * g4 + 0] * rstd * gg.x * siluf_(bf2f(gt.x)), O[vt][4 * g4 + 1] * rstd * gg.y * siluf_(bf2f(gt.y)));
;           o.y = pk2(O[vt][4 * g4 + 2] * rstd * gg.z * siluf_(bf2f(gt.z)), O[vt][4 * g4 + 3] * rstd * gg.w * siluf_(bf2f(gt.w)));
;           *(uint2*)(MIX + kblk((int)qrow, hd * 64 + v0, ROWS)) = o;
;         }
.LBB0_588:
	s_or_b64 exec, exec, s[0:1]
	s_movk_i32 s0, 0x80
	v_cmp_gt_u32_e32 vcc, s0, v196
	s_waitcnt lgkmcnt(0)
	s_barrier
	s_and_saveexec_b64 s[0:1], vcc
	s_xor_b64 s[0:1], exec, s[0:1]
	s_cbranch_execz .LBB0_590
	s_waitcnt vmcnt(0)
	v_div_scale_f32 v32, s[8:9], v160, v160, 1.0
	v_rcp_f32_e32 v33, v32
	s_add_u32 s4, s40, 0x1dc6000
	s_addc_u32 s5, s41, 0
	s_lshl_b32 s2, s7, 1
	v_fma_f32 v34, -v32, v33, 1.0
	v_fmac_f32_e32 v33, v34, v33
	v_div_scale_f32 v34, vcc, 1.0, v160, 1.0
	v_mul_f32_e32 v35, v34, v33
	v_fma_f32 v36, -v32, v35, v34
	v_fmac_f32_e32 v35, v36, v33
	v_fma_f32 v32, -v32, v35, v34
	v_div_fmas_f32 v32, v32, v33, v35
	v_div_fixup_f32 v44, v32, v160, 1.0
	ds_read2_b32 v[32:33], v197 offset0:56 offset1:57
	s_mul_i32 s6, s6, 0x9000
	v_add_lshl_u32 v160, v165, s6, 6
	v_mov_b32_e32 v165, v161
	s_mov_b64 s[6:7], 0x1a20
	s_waitcnt lgkmcnt(0)
	v_pk_fma_f32 v[34:35], v[12:13], v[44:45], v[32:33] op_sel_hi:[1,0,1] neg_lo:[0,0,1] neg_hi:[0,0,1]
	ds_read2_b32 v[12:13], v197 offset0:58 offset1:59
	ds_read2_b32 v[82:83], v197 offset0:48 offset1:49
	ds_read2_b32 v[48:49], v197 offset1:1
	v_readlane_b32 s8, v254, 27
	v_readlane_b32 s9, v254, 28
	s_waitcnt lgkmcnt(2)
	v_pk_fma_f32 v[32:33], v[14:15], v[44:45], v[12:13] op_sel_hi:[1,0,1] neg_lo:[0,0,1] neg_hi:[0,0,1]
	ds_read2_b32 v[14:15], v197 offset0:2 offset1:3
	v_lshl_add_u64 v[12:13], v[166:167], 0, s[2:3]
	v_lshl_add_u64 v[12:13], v[12:13], 0, v[164:165]
	v_lshl_add_u64 v[36:37], v[12:13], 0, s[6:7]
	global_load_dwordx2 v[204:205], v[36:37], off
	global_load_dwordx2 v[206:207], v[36:37], off offset:16
	global_load_dwordx2 v[208:209], v[36:37], off offset:32
	global_load_dwordx2 v[210:211], v[36:37], off offset:48
	global_load_dwordx2 v[212:213], v[36:37], off offset:64
	global_load_dwordx2 v[214:215], v[36:37], off offset:80
	global_load_dwordx2 v[216:217], v[36:37], off offset:96
	global_load_dwordx2 v[218:219], v[36:37], off offset:112
	global_load_dwordx4 v[220:223], v171, s[8:9]
	global_load_dwordx4 v[224:227], v171, s[8:9] offset:32
	global_load_dwordx4 v[228:231], v171, s[8:9] offset:64
	global_load_dwordx4 v[232:235], v171, s[8:9] offset:96
	global_load_dwordx4 v[236:239], v171, s[8:9] offset:128
	global_load_dwordx4 v[240:243], v171, s[8:9] offset:160
	global_load_dwordx4 v[244:247], v171, s[8:9] offset:192
	global_load_dwordx4 v[248:251], v171, s[8:9] offset:224
	v_add_co_u32_e32 v12, vcc, s16, v12
	s_waitcnt lgkmcnt(0)
	v_pk_fma_f32 v[46:47], v[18:19], v[44:45], v[14:15] op_sel_hi:[1,0,1] neg_lo:[0,0,1] neg_hi:[0,0,1]
	v_addc_co_u32_e32 v13, vcc, 0, v13, vcc
	s_nop 0
	v_pk_fma_f32 v[48:49], v[16:17], v[44:45], v[48:49] op_sel_hi:[1,0,1] neg_lo:[0,0,1] neg_hi:[0,0,1]
	s_nop 0
	v_pk_mul_f32 v[56:57], v[48:49], v[48:49]
	v_pk_mul_f32 v[52:53], v[46:47], v[46:47]
	v_add_f32_e32 v56, v56, v57
	v_add_f32_e32 v52, v56, v52
	v_add_f32_e32 v52, v52, v53
	v_lshl_add_u64 v[38:39], s[4:5], 0, v[160:161]
	v_add_u32_e32 v160, 0x120000, v160
	v_pk_mul_f32 v[40:41], v[34:35], v[34:35]
	v_pk_mul_f32 v[42:43], v[32:33], v[32:33]
	v_lshl_add_u64 v[38:39], v[38:39], 0, v[164:165]
	s_waitcnt vmcnt(0) lgkmcnt(0)
	v_mov_b32_e32 v18, v204
	v_mov_b32_e32 v19, v205
	v_mov_b32_e32 v12, v220
	v_mov_b32_e32 v13, v221
	v_mov_b32_e32 v14, v222
	v_mov_b32_e32 v15, v223
	v_and_b32_e32 v45, 0xffff0000, v18
	v_lshlrev_b32_e32 v18, 16, v18
	v_mul_f32_e32 v16, 0xbfb8aa3b, v18
	v_mul_f32_e32 v17, 0xbfb8aa3b, v45
	v_exp_f32_e32 v16, v16
	v_exp_f32_e32 v17, v17
	s_nop 0
	v_pk_add_f32 v[16:17], v[16:17], 1.0 op_sel_hi:[1,0]
	s_nop 0
	v_div_scale_f32 v50, s[6:7], v17, v17, v45
	v_rcp_f32_e32 v51, v50
	s_nop 0
	v_fma_f32 v54, -v50, v51, 1.0
	v_fmac_f32_e32 v51, v54, v51
	v_div_scale_f32 v54, vcc, v45, v17, v45
	v_mul_f32_e32 v55, v54, v51
	v_fma_f32 v58, -v50, v55, v54
	v_fmac_f32_e32 v55, v58, v51
	v_fma_f32 v50, -v50, v55, v54
	v_div_fmas_f32 v50, v50, v51, v55
	v_div_fixup_f32 v51, v50, v17, v45
	v_div_scale_f32 v17, s[6:7], v16, v16, v18
	v_rcp_f32_e32 v45, v17
	s_nop 0
	v_fma_f32 v50, -v17, v45, 1.0
	v_fmac_f32_e32 v45, v50, v45
	v_div_scale_f32 v50, vcc, v18, v16, v18
	v_mul_f32_e32 v54, v50, v45
	v_fma_f32 v55, -v17, v54, v50
	v_fmac_f32_e32 v54, v55, v45
	v_fma_f32 v17, -v17, v54, v50
	v_div_fmas_f32 v17, v17, v45, v54
	v_div_fixup_f32 v50, v17, v16, v18
	v_and_b32_e32 v18, 0xffff0000, v19
	v_lshlrev_b32_e32 v19, 16, v19
	v_mul_f32_e32 v16, 0xbfb8aa3b, v19
	v_mul_f32_e32 v17, 0xbfb8aa3b, v18
	v_exp_f32_e32 v16, v16
	v_exp_f32_e32 v17, v17
	s_nop 0
	v_pk_add_f32 v[16:17], v[16:17], 1.0 op_sel_hi:[1,0]
	s_nop 0
	v_div_scale_f32 v45, s[6:7], v17, v17, v18
	v_rcp_f32_e32 v54, v45
	s_nop 0
	v_fma_f32 v55, -v45, v54, 1.0
	v_fmac_f32_e32 v54, v55, v54
	v_div_scale_f32 v55, vcc, v18, v17, v18
	v_mul_f32_e32 v58, v55, v54
	v_fma_f32 v59, -v45, v58, v55
	v_fmac_f32_e32 v58, v59, v54
	v_fma_f32 v45, -v45, v58, v55
	v_div_fmas_f32 v45, v45, v54, v58
	v_div_fixup_f32 v55, v45, v17, v18
	v_div_scale_f32 v17, s[6:7], v16, v16, v19
	v_rcp_f32_e32 v18, v17
	s_nop 0
	v_fma_f32 v45, -v17, v18, 1.0
	v_fmac_f32_e32 v18, v45, v18
	v_div_scale_f32 v45, vcc, v19, v16, v19
	v_mul_f32_e32 v54, v45, v18
	v_fma_f32 v58, -v17, v54, v45
	v_fmac_f32_e32 v54, v58, v18
	v_fma_f32 v17, -v17, v54, v45
	v_div_fmas_f32 v17, v17, v18, v54
	v_div_fixup_f32 v54, v17, v16, v19
	ds_read2_b32 v[16:17], v197 offset0:10 offset1:11
	ds_read2_b32 v[18:19], v197 offset0:8 offset1:9
	s_waitcnt lgkmcnt(1)
	v_pk_fma_f32 v[60:61], v[22:23], v[44:45], v[16:17] op_sel_hi:[1,0,1] neg_lo:[0,0,1] neg_hi:[0,0,1]
	s_nop 0
	s_waitcnt lgkmcnt(0)
; DI size_t kblk(int row, int col, int nrows) { return ((size_t)(col >> 5) * nrows + row) * 32 + (col & 31); }
; DI float bf2f(bf16_t v) { return __uint_as_float(((unsigned)v) << 16); }
; DI unsigned pk2(float a, float b) { hwf32x2 f = {a, b}; hwbf16x2 r = __builtin_convertvector(f, hwbf16x2); return __builtin_bit_cast(unsigned, r); }
; DI float siluf_(float z) { return z / (1.f + __expf(-z)); }
; DI int crow(int reg, int h) { return (reg & 3) + 8 * (reg >> 2) + 4 * h; }
; template <int MODE>
; DI void attn_mfma(const Params& p, int l, int b, int hd, int qb, unsigned char* smem) {
;     ...
; #pragma unroll
;       for (int vt = 0; vt < 2; ++vt)
; #pragma unroll
;         for (int i = 0; i < 16; ++i) { const float o = O[vt][i] * i0 - sO[ql * 65 + vt * 32 + crow(i, h2)]; O[vt][i] = o; ss += o * o; }
;       ss += __shfl_xor(ss, 32);
;       const float rstd = rsqrtf(ss * (1.f / 64.f) + EPS) * (1.f - lam_init);
; #pragma unroll
;       for (int vt = 0; vt < 2; ++vt)
; #pragma unroll
;         for (int g4 = 0; g4 < 4; ++g4) {
;           const int v0 = vt * 32 + 8 * g4 + 4 * h2;
;           const ushort4 gt = *(const ushort4*)(P + qrow * PW + GATE + hd * 64 + v0);
;           const float4 gg = *(const float4*)(p.diff_g + l * 64 + v0);
;           uint2 o;
;           o.x = pk2(O[vt][4 * g4 + 0] * rstd * gg.x * siluf_(bf2f(gt.x)), O[vt][4 * g4 + 1] * rstd * gg.y * siluf_(bf2f(gt.y)));
;           o.y = pk2(O[vt][4 * g4 + 2] * rstd * gg.z * siluf_(bf2f(gt.z)), O[vt][4 * g4 + 3] * rstd * gg.w * siluf_(bf2f(gt.w)));
;           *(uint2*)(MIX + kblk((int)qrow, hd * 64 + v0, ROWS)) = o;
;         }
	v_pk_fma_f32 v[62:63], v[20:21], v[44:45], v[18:19] op_sel_hi:[1,0,1] neg_lo:[0,0,1] neg_hi:[0,0,1]
	v_pk_mul_f32 v[68:69], v[60:61], v[60:61]
	v_pk_mul_f32 v[70:71], v[62:63], v[62:63]
	s_nop 0
	v_mov_b32_e32 v16, v206
	v_mov_b32_e32 v17, v207
	v_and_b32_e32 v20, 0xffff0000, v16
	v_lshlrev_b32_e32 v16, 16, v16
	v_mul_f32_e32 v18, 0xbfb8aa3b, v16
	v_mul_f32_e32 v19, 0xbfb8aa3b, v20
	v_exp_f32_e32 v18, v18
	v_exp_f32_e32 v19, v19
	v_add_f32_e32 v52, v52, v70
	v_add_f32_e32 v52, v52, v71
	v_add_f32_e32 v52, v52, v68
	v_pk_add_f32 v[18:19], v[18:19], 1.0 op_sel_hi:[1,0]
	v_add_f32_e32 v52, v52, v69
	v_div_scale_f32 v21, s[6:7], v19, v19, v20
	v_rcp_f32_e32 v22, v21
	s_nop 0
	v_fma_f32 v23, -v21, v22, 1.0
	v_fmac_f32_e32 v22, v23, v22
	v_div_scale_f32 v23, vcc, v20, v19, v20
	v_mul_f32_e32 v45, v23, v22
	v_fma_f32 v58, -v21, v45, v23
	v_fmac_f32_e32 v45, v58, v22
	v_fma_f32 v21, -v21, v45, v23
	v_div_fmas_f32 v21, v21, v22, v45
	v_div_fixup_f32 v65, v21, v19, v20
	v_div_scale_f32 v19, s[6:7], v18, v18, v16
	v_rcp_f32_e32 v20, v19
	s_nop 0
	v_fma_f32 v21, -v19, v20, 1.0
	v_fmac_f32_e32 v20, v21, v20
	v_div_scale_f32 v21, vcc, v16, v18, v16
	v_mul_f32_e32 v22, v21, v20
	v_fma_f32 v23, -v19, v22, v21
	v_fmac_f32_e32 v22, v23, v20
	v_fma_f32 v19, -v19, v22, v21
	v_div_fmas_f32 v19, v19, v20, v22
	v_div_fixup_f32 v64, v19, v18, v16
	v_and_b32_e32 v18, 0xffff0000, v17
	v_lshlrev_b32_e32 v19, 16, v17
	v_mul_f32_e32 v16, 0xbfb8aa3b, v19
	v_mul_f32_e32 v17, 0xbfb8aa3b, v18
	v_exp_f32_e32 v16, v16
	v_exp_f32_e32 v17, v17
	s_nop 0
	v_pk_add_f32 v[16:17], v[16:17], 1.0 op_sel_hi:[1,0]
	s_nop 0
	v_div_scale_f32 v20, s[6:7], v17, v17, v18
	v_rcp_f32_e32 v21, v20
	s_nop 0
	v_fma_f32 v22, -v20, v21, 1.0
	v_fmac_f32_e32 v21, v22, v21
	v_div_scale_f32 v22, vcc, v18, v17, v18
	v_mul_f32_e32 v23, v22, v21
	v_fma_f32 v45, -v20, v23, v22
	v_fmac_f32_e32 v23, v45, v21
	v_fma_f32 v20, -v20, v23, v22
	v_div_fmas_f32 v20, v20, v21, v23
	v_div_fixup_f32 v67, v20, v17, v18
	v_div_scale_f32 v17, s[6:7], v16, v16, v19
	v_rcp_f32_e32 v18, v17
	v_pk_fma_f32 v[8:9], v[8:9], v[44:45], v[82:83] op_sel_hi:[1,0,1] neg_lo:[0,0,1] neg_hi:[0,0,1]
	v_fma_f32 v20, -v17, v18, 1.0
	v_fmac_f32_e32 v18, v20, v18
	v_div_scale_f32 v20, vcc, v19, v16, v19
	v_mul_f32_e32 v21, v20, v18
	v_fma_f32 v22, -v17, v21, v20
	v_fmac_f32_e32 v21, v22, v18
	v_fma_f32 v17, -v17, v21, v20
	v_div_fmas_f32 v17, v17, v18, v21
	v_div_fixup_f32 v66, v17, v16, v19
	ds_read2_b32 v[16:17], v197 offset0:18 offset1:19
	ds_read2_b32 v[18:19], v197 offset0:34 offset1:35
	s_waitcnt lgkmcnt(1)
	v_pk_fma_f32 v[26:27], v[26:27], v[44:45], v[16:17] op_sel_hi:[1,0,1] neg_lo:[0,0,1] neg_hi:[0,0,1]
	ds_read2_b32 v[16:17], v197 offset0:16 offset1:17
	s_waitcnt lgkmcnt(1)
	v_pk_fma_f32 v[18:19], v[2:3], v[44:45], v[18:19] op_sel_hi:[1,0,1] neg_lo:[0,0,1] neg_hi:[0,0,1]
	ds_read2_b32 v[2:3], v197 offset0:32 offset1:33
	v_pk_mul_f32 v[72:73], v[26:27], v[26:27]
	s_waitcnt lgkmcnt(1)
	v_pk_fma_f32 v[58:59], v[24:25], v[44:45], v[16:17] op_sel_hi:[1,0,1] neg_lo:[0,0,1] neg_hi:[0,0,1]
	ds_read2_b32 v[16:17], v197 offset0:26 offset1:27
	s_waitcnt lgkmcnt(1)
	v_pk_fma_f32 v[20:21], v[0:1], v[44:45], v[2:3] op_sel_hi:[1,0,1] neg_lo:[0,0,1] neg_hi:[0,0,1]
	ds_read2_b32 v[2:3], v197 offset0:42 offset1:43
	v_pk_mul_f32 v[74:75], v[58:59], v[58:59]
	v_pk_mul_f32 v[80:81], v[20:21], v[20:21]
	s_waitcnt lgkmcnt(1)
	v_pk_fma_f32 v[22:23], v[30:31], v[44:45], v[16:17] op_sel_hi:[1,0,1] neg_lo:[0,0,1] neg_hi:[0,0,1]
	ds_read2_b32 v[16:17], v197 offset0:24 offset1:25
	v_add_f32_e32 v52, v52, v74
	v_add_f32_e32 v52, v52, v75
	s_waitcnt lgkmcnt(1)
	v_pk_fma_f32 v[6:7], v[6:7], v[44:45], v[2:3] op_sel_hi:[1,0,1] neg_lo:[0,0,1] neg_hi:[0,0,1]
	ds_read2_b32 v[2:3], v197 offset0:40 offset1:41
	s_waitcnt lgkmcnt(1)
	v_pk_fma_f32 v[24:25], v[28:29], v[44:45], v[16:17] op_sel_hi:[1,0,1] neg_lo:[0,0,1] neg_hi:[0,0,1]
	v_add_f32_e32 v52, v52, v72
	v_pk_mul_f32 v[76:77], v[24:25], v[24:25]
	v_add_f32_e32 v52, v52, v73
	v_add_f32_e32 v52, v52, v76
	v_pk_mul_f32 v[30:31], v[22:23], v[22:23]
	v_add_f32_e32 v52, v52, v77
	v_add_f32_e32 v30, v52, v30
	v_add_f32_e32 v30, v30, v31
	v_add_f32_e32 v30, v30, v80
	v_lshl_add_u64 v[16:17], s[4:5], 0, v[160:161]
	v_pk_mul_f32 v[28:29], v[18:19], v[18:19]
	v_add_f32_e32 v30, v30, v81
	v_lshl_add_u64 v[0:1], v[16:17], 0, v[164:165]
	s_waitcnt lgkmcnt(0)
	v_pk_fma_f32 v[16:17], v[4:5], v[44:45], v[2:3] op_sel_hi:[1,0,1] neg_lo:[0,0,1] neg_hi:[0,0,1]
	ds_read2_b32 v[2:3], v197 offset0:50 offset1:51
	v_add_f32_e32 v28, v30, v28
	v_pk_mul_f32 v[4:5], v[16:17], v[16:17]
	v_add_f32_e32 v28, v28, v29
	v_add_f32_e32 v4, v28, v4
	v_pk_mul_f32 v[78:79], v[6:7], v[6:7]
	v_add_f32_e32 v4, v4, v5
	v_add_f32_e32 v4, v4, v78
	s_waitcnt lgkmcnt(0)
	v_pk_fma_f32 v[2:3], v[10:11], v[44:45], v[2:3] op_sel_hi:[1,0,1] neg_lo:[0,0,1] neg_hi:[0,0,1]
	v_pk_mul_f32 v[44:45], v[8:9], v[8:9]
	v_add_f32_e32 v4, v4, v79
	v_add_f32_e32 v4, v4, v44
	v_pk_mul_f32 v[10:11], v[2:3], v[2:3]
	v_add_f32_e32 v4, v4, v45
	v_add_f32_e32 v4, v4, v10
	v_add_f32_e32 v4, v4, v11
	v_add_f32_e32 v4, v4, v40
	v_add_f32_e32 v4, v4, v41
	v_add_f32_e32 v4, v4, v42
	v_add_f32_e32 v4, v4, v43
	ds_bpermute_b32 v5, v170, v4
	s_waitcnt lgkmcnt(0)
; DI size_t kblk(int row, int col, int nrows) { return ((size_t)(col >> 5) * nrows + row) * 32 + (col & 31); }
; DI float bf2f(bf16_t v) { return __uint_as_float(((unsigned)v) << 16); }
; DI unsigned pk2(float a, float b) { hwf32x2 f = {a, b}; hwbf16x2 r = __builtin_convertvector(f, hwbf16x2); return __builtin_bit_cast(unsigned, r); }
; DI float siluf_(float z) { return z / (1.f + __expf(-z)); }
; template <int MODE>
; DI void attn_mfma(const Params& p, int l, int b, int hd, int qb, unsigned char* smem) {
;     ...
;       const float rstd = rsqrtf(ss * (1.f / 64.f) + EPS) * (1.f - lam_init);
; #pragma unroll
;       for (int vt = 0; vt < 2; ++vt)
; #pragma unroll
;         for (int g4 = 0; g4 < 4; ++g4) {
;           const int v0 = vt * 32 + 8 * g4 + 4 * h2;
;           const ushort4 gt = *(const ushort4*)(P + qrow * PW + GATE + hd * 64 + v0);
;           const float4 gg = *(const float4*)(p.diff_g + l * 64 + v0);
;           uint2 o;
;           o.x = pk2(O[vt][4 * g4 + 0] * rstd * gg.x * siluf_(bf2f(gt.x)), O[vt][4 * g4 + 1] * rstd * gg.y * siluf_(bf2f(gt.y)));
;           o.y = pk2(O[vt][4 * g4 + 2] * rstd * gg.z * siluf_(bf2f(gt.z)), O[vt][4 * g4 + 3] * rstd * gg.w * siluf_(bf2f(gt.w)));
;           *(uint2*)(MIX + kblk((int)qrow, hd * 64 + v0, ROWS)) = o;
;         }
	v_add_f32_e32 v4, v4, v5
	v_fmamk_f32 v4, v4, 0x3c800000, v162
	v_cmp_gt_f32_e32 vcc, s38, v4
	v_mul_f32_e32 v5, 0x4b800000, v4
	s_nop 0
	v_cndmask_b32_e32 v4, v4, v5, vcc
	v_rsq_f32_e32 v4, v4
	s_nop 0
	v_mul_f32_e32 v5, 0x45800000, v4
	v_cndmask_b32_e32 v4, v4, v5, vcc
	v_mul_f32_e32 v4, v169, v4
	v_pk_mul_f32 v[10:11], v[48:49], v[4:5] op_sel_hi:[1,0]
	s_nop 0
	v_pk_mul_f32 v[10:11], v[12:13], v[10:11]
	v_pk_mul_f32 v[12:13], v[46:47], v[4:5] op_sel_hi:[1,0]
	v_pk_mul_f32 v[10:11], v[50:51], v[10:11]
	v_pk_mul_f32 v[12:13], v[14:15], v[12:13]
	v_cvt_pk_bf16_f32 v10, v10, v11
	v_pk_mul_f32 v[12:13], v[54:55], v[12:13]
	v_pk_mul_f32 v[14:15], v[62:63], v[4:5] op_sel_hi:[1,0]
	v_cvt_pk_bf16_f32 v11, v12, v13
	global_store_dwordx2 v[38:39], v[10:11], off
	s_nop 0
	s_nop 0
	v_mov_b32_e32 v10, v224
	v_mov_b32_e32 v11, v225
	v_mov_b32_e32 v12, v226
	v_mov_b32_e32 v13, v227
	v_pk_mul_f32 v[10:11], v[14:15], v[10:11]
	v_pk_mul_f32 v[14:15], v[60:61], v[4:5] op_sel_hi:[1,0]
	v_pk_mul_f32 v[10:11], v[10:11], v[64:65]
	v_pk_mul_f32 v[12:13], v[14:15], v[12:13]
	v_cvt_pk_bf16_f32 v10, v10, v11
	v_pk_mul_f32 v[12:13], v[12:13], v[66:67]
	s_nop 0
	v_cvt_pk_bf16_f32 v11, v12, v13
	global_store_dwordx2 v[38:39], v[10:11], off offset:16
	s_nop 0
	s_nop 0
	s_nop 0
	s_waitcnt lgkmcnt(0)
	v_mov_b32_e32 v14, v208
	v_mov_b32_e32 v15, v209
	v_mov_b32_e32 v10, v228
	v_mov_b32_e32 v11, v229
	v_mov_b32_e32 v12, v230
	v_mov_b32_e32 v13, v231
	v_and_b32_e32 v5, 0xffff0000, v14
	v_lshlrev_b32_e32 v14, 16, v14
	v_mul_f32_e32 v28, 0xbfb8aa3b, v14
	v_mul_f32_e32 v29, 0xbfb8aa3b, v5
	v_exp_f32_e32 v28, v28
	v_exp_f32_e32 v29, v29
	v_pk_mul_f32 v[30:31], v[58:59], v[4:5] op_sel_hi:[1,0]
	v_pk_add_f32 v[28:29], v[28:29], 1.0 op_sel_hi:[1,0]
	v_pk_mul_f32 v[10:11], v[30:31], v[10:11]
	v_div_scale_f32 v30, s[4:5], v29, v29, v5
	v_rcp_f32_e32 v31, v30
	s_nop 0
	v_fma_f32 v40, -v30, v31, 1.0
	v_fmac_f32_e32 v31, v40, v31
	v_div_scale_f32 v40, vcc, v5, v29, v5
	v_mul_f32_e32 v41, v40, v31
	v_fma_f32 v42, -v30, v41, v40
	v_fmac_f32_e32 v41, v42, v31
	v_fma_f32 v30, -v30, v41, v40
	v_div_fmas_f32 v30, v30, v31, v41
	v_div_fixup_f32 v29, v30, v29, v5
	v_div_scale_f32 v5, s[4:5], v28, v28, v14
	v_rcp_f32_e32 v30, v5
	s_nop 0
	v_fma_f32 v31, -v5, v30, 1.0
	v_fmac_f32_e32 v30, v31, v30
	v_div_scale_f32 v31, vcc, v14, v28, v14
	v_mul_f32_e32 v40, v31, v30
	v_fma_f32 v41, -v5, v40, v31
	v_fmac_f32_e32 v40, v41, v30
	v_fma_f32 v5, -v5, v40, v31
	v_div_fmas_f32 v5, v5, v30, v40
	v_div_fixup_f32 v28, v5, v28, v14
	v_pk_mul_f32 v[10:11], v[10:11], v[28:29]
	v_and_b32_e32 v5, 0xffff0000, v15
	v_cvt_pk_bf16_f32 v10, v10, v11
	v_lshlrev_b32_e32 v11, 16, v15
	v_mul_f32_e32 v14, 0xbfb8aa3b, v11
	v_mul_f32_e32 v15, 0xbfb8aa3b, v5
	v_exp_f32_e32 v14, v14
	v_exp_f32_e32 v15, v15
	v_pk_mul_f32 v[26:27], v[26:27], v[4:5] op_sel_hi:[1,0]
	v_pk_add_f32 v[14:15], v[14:15], 1.0 op_sel_hi:[1,0]
	v_pk_mul_f32 v[12:13], v[26:27], v[12:13]
	v_div_scale_f32 v26, s[4:5], v15, v15, v5
	v_rcp_f32_e32 v27, v26
	s_nop 0
	v_fma_f32 v28, -v26, v27, 1.0
	v_fmac_f32_e32 v27, v28, v27
	v_div_scale_f32 v28, vcc, v5, v15, v5
	v_mul_f32_e32 v29, v28, v27
	v_fma_f32 v30, -v26, v29, v28
	v_fmac_f32_e32 v29, v30, v27
	v_fma_f32 v26, -v26, v29, v28
	v_div_fmas_f32 v26, v26, v27, v29
	v_div_fixup_f32 v15, v26, v15, v5
	v_div_scale_f32 v5, s[4:5], v14, v14, v11
	v_rcp_f32_e32 v26, v5
	s_nop 0
	v_fma_f32 v27, -v5, v26, 1.0
	v_fmac_f32_e32 v26, v27, v26
	v_div_scale_f32 v27, vcc, v11, v14, v11
	v_mul_f32_e32 v28, v27, v26
	v_fma_f32 v29, -v5, v28, v27
	v_fmac_f32_e32 v28, v29, v26
	v_fma_f32 v5, -v5, v28, v27
	v_div_fmas_f32 v5, v5, v26, v28
	v_div_fixup_f32 v14, v5, v14, v11
	v_pk_mul_f32 v[12:13], v[12:13], v[14:15]
	s_nop 0
	v_cvt_pk_bf16_f32 v11, v12, v13
	global_store_dwordx2 v[38:39], v[10:11], off offset:32
	s_nop 0
	s_nop 0
	s_nop 0
	s_waitcnt lgkmcnt(0)
	v_mov_b32_e32 v14, v210
	v_mov_b32_e32 v15, v211
	v_mov_b32_e32 v10, v232
	v_mov_b32_e32 v11, v233
	v_mov_b32_e32 v12, v234
	v_mov_b32_e32 v13, v235
	v_and_b32_e32 v5, 0xffff0000, v14
	v_lshlrev_b32_e32 v14, 16, v14
	v_pk_mul_f32 v[24:25], v[24:25], v[4:5] op_sel_hi:[1,0]
	v_mul_f32_e32 v26, 0xbfb8aa3b, v14
	v_pk_mul_f32 v[10:11], v[24:25], v[10:11]
	v_mul_f32_e32 v24, 0xbfb8aa3b, v5
	v_exp_f32_e32 v26, v26
	v_exp_f32_e32 v27, v24
	s_nop 0
	v_pk_add_f32 v[24:25], v[26:27], 1.0 op_sel_hi:[1,0]
	s_nop 0
	v_div_scale_f32 v26, s[4:5], v25, v25, v5
	v_rcp_f32_e32 v27, v26
	s_nop 0
	v_fma_f32 v28, -v26, v27, 1.0
	v_fmac_f32_e32 v27, v28, v27
	v_div_scale_f32 v28, vcc, v5, v25, v5
	v_mul_f32_e32 v29, v28, v27
	v_fma_f32 v30, -v26, v29, v28
	v_fmac_f32_e32 v29, v30, v27
	v_fma_f32 v26, -v26, v29, v28
	v_div_fmas_f32 v26, v26, v27, v29
	v_div_fixup_f32 v25, v26, v25, v5
	v_div_scale_f32 v5, s[4:5], v24, v24, v14
	v_rcp_f32_e32 v26, v5
	s_nop 0
	v_fma_f32 v27, -v5, v26, 1.0
	v_fmac_f32_e32 v26, v27, v26
	v_div_scale_f32 v27, vcc, v14, v24, v14
	v_mul_f32_e32 v28, v27, v26
	v_fma_f32 v29, -v5, v28, v27
	v_fmac_f32_e32 v28, v29, v26
	v_fma_f32 v5, -v5, v28, v27
	v_div_fmas_f32 v5, v5, v26, v28
	v_div_fixup_f32 v24, v5, v24, v14
	v_pk_mul_f32 v[10:11], v[10:11], v[24:25]
	v_and_b32_e32 v5, 0xffff0000, v15
	v_cvt_pk_bf16_f32 v10, v10, v11
	v_lshlrev_b32_e32 v11, 16, v15
	v_mul_f32_e32 v14, 0xbfb8aa3b, v11
	v_mul_f32_e32 v15, 0xbfb8aa3b, v5
	v_exp_f32_e32 v14, v14
	v_exp_f32_e32 v15, v15
	v_pk_mul_f32 v[22:23], v[22:23], v[4:5] op_sel_hi:[1,0]
	v_pk_add_f32 v[14:15], v[14:15], 1.0 op_sel_hi:[1,0]
	v_pk_mul_f32 v[12:13], v[22:23], v[12:13]
	v_div_scale_f32 v22, s[4:5], v15, v15, v5
	v_rcp_f32_e32 v23, v22
	s_nop 0
	v_fma_f32 v24, -v22, v23, 1.0
	v_fmac_f32_e32 v23, v24, v23
	v_div_scale_f32 v24, vcc, v5, v15, v5
	v_mul_f32_e32 v25, v24, v23
	v_fma_f32 v26, -v22, v25, v24
	v_fmac_f32_e32 v25, v26, v23
	v_fma_f32 v22, -v22, v25, v24
	v_div_fmas_f32 v22, v22, v23, v25
	v_div_fixup_f32 v15, v22, v15, v5
	v_div_scale_f32 v5, s[4:5], v14, v14, v11
	v_rcp_f32_e32 v22, v5
	s_nop 0
	v_fma_f32 v23, -v5, v22, 1.0
	v_fmac_f32_e32 v22, v23, v22
	v_div_scale_f32 v23, vcc, v11, v14, v11
	v_mul_f32_e32 v24, v23, v22
	v_fma_f32 v25, -v5, v24, v23
	v_fmac_f32_e32 v24, v25, v22
	v_fma_f32 v5, -v5, v24, v23
	v_div_fmas_f32 v5, v5, v22, v24
	v_div_fixup_f32 v14, v5, v14, v11
	v_pk_mul_f32 v[12:13], v[12:13], v[14:15]
	s_nop 0
	v_cvt_pk_bf16_f32 v11, v12, v13
	global_store_dwordx2 v[38:39], v[10:11], off offset:48
	s_nop 0
	s_nop 0
	s_nop 0
	s_waitcnt lgkmcnt(0)
; DI size_t kblk(int row, int col, int nrows) { return ((size_t)(col >> 5) * nrows + row) * 32 + (col & 31); }
; DI float bf2f(bf16_t v) { return __uint_as_float(((unsigned)v) << 16); }
; DI unsigned pk2(float a, float b) { hwf32x2 f = {a, b}; hwbf16x2 r = __builtin_convertvector(f, hwbf16x2); return __builtin_bit_cast(unsigned, r); }
; DI float siluf_(float z) { return z / (1.f + __expf(-z)); }
; template <int MODE>
; DI void attn_mfma(const Params& p, int l, int b, int hd, int qb, unsigned char* smem) {
;     ...
;         for (int g4 = 0; g4 < 4; ++g4) {
;           const int v0 = vt * 32 + 8 * g4 + 4 * h2;
;           const ushort4 gt = *(const ushort4*)(P + qrow * PW + GATE + hd * 64 + v0);
;           const float4 gg = *(const float4*)(p.diff_g + l * 64 + v0);
;           uint2 o;
;           o.x = pk2(O[vt][4 * g4 + 0] * rstd * gg.x * siluf_(bf2f(gt.x)), O[vt][4 * g4 + 1] * rstd * gg.y * siluf_(bf2f(gt.y)));
;           o.y = pk2(O[vt][4 * g4 + 2] * rstd * gg.z * siluf_(bf2f(gt.z)), O[vt][4 * g4 + 3] * rstd * gg.w * siluf_(bf2f(gt.w)));
;           *(uint2*)(MIX + kblk((int)qrow, hd * 64 + v0, ROWS)) = o;
;         }
	v_mov_b32_e32 v10, v212
	v_mov_b32_e32 v11, v213
	v_mov_b32_e32 v12, v236
	v_mov_b32_e32 v13, v237
	v_mov_b32_e32 v14, v238
	v_mov_b32_e32 v15, v239
	v_and_b32_e32 v5, 0xffff0000, v10
	v_lshlrev_b32_e32 v10, 16, v10
	v_pk_mul_f32 v[20:21], v[20:21], v[4:5] op_sel_hi:[1,0]
	v_mul_f32_e32 v22, 0xbfb8aa3b, v10
	v_pk_mul_f32 v[12:13], v[20:21], v[12:13]
	v_mul_f32_e32 v20, 0xbfb8aa3b, v5
	v_exp_f32_e32 v22, v22
	v_exp_f32_e32 v23, v20
	s_nop 0
	v_pk_add_f32 v[20:21], v[22:23], 1.0 op_sel_hi:[1,0]
	s_nop 0
	v_div_scale_f32 v22, s[4:5], v21, v21, v5
	v_rcp_f32_e32 v23, v22
	s_nop 0
	v_fma_f32 v24, -v22, v23, 1.0
	v_fmac_f32_e32 v23, v24, v23
	v_div_scale_f32 v24, vcc, v5, v21, v5
	v_mul_f32_e32 v25, v24, v23
	v_fma_f32 v26, -v22, v25, v24
	v_fmac_f32_e32 v25, v26, v23
	v_fma_f32 v22, -v22, v25, v24
	v_div_fmas_f32 v22, v22, v23, v25
	v_div_fixup_f32 v21, v22, v21, v5
	v_div_scale_f32 v5, s[4:5], v20, v20, v10
	v_rcp_f32_e32 v22, v5
	s_nop 0
	v_fma_f32 v23, -v5, v22, 1.0
	v_fmac_f32_e32 v22, v23, v22
	v_div_scale_f32 v23, vcc, v10, v20, v10
	v_mul_f32_e32 v24, v23, v22
	v_fma_f32 v25, -v5, v24, v23
	v_fmac_f32_e32 v24, v25, v22
	v_fma_f32 v5, -v5, v24, v23
	v_div_fmas_f32 v5, v5, v22, v24
	v_div_fixup_f32 v20, v5, v20, v10
	v_pk_mul_f32 v[12:13], v[12:13], v[20:21]
	v_and_b32_e32 v5, 0xffff0000, v11
	v_lshlrev_b32_e32 v11, 16, v11
	v_cvt_pk_bf16_f32 v10, v12, v13
	v_mul_f32_e32 v12, 0xbfb8aa3b, v11
	v_mul_f32_e32 v13, 0xbfb8aa3b, v5
	v_exp_f32_e32 v12, v12
	v_exp_f32_e32 v13, v13
	v_pk_mul_f32 v[18:19], v[18:19], v[4:5] op_sel_hi:[1,0]
	v_pk_add_f32 v[12:13], v[12:13], 1.0 op_sel_hi:[1,0]
	v_pk_mul_f32 v[14:15], v[18:19], v[14:15]
	v_div_scale_f32 v18, s[4:5], v13, v13, v5
	v_rcp_f32_e32 v19, v18
	s_nop 0
	v_fma_f32 v20, -v18, v19, 1.0
	v_fmac_f32_e32 v19, v20, v19
	v_div_scale_f32 v20, vcc, v5, v13, v5
	v_mul_f32_e32 v21, v20, v19
	v_fma_f32 v22, -v18, v21, v20
	v_fmac_f32_e32 v21, v22, v19
	v_fma_f32 v18, -v18, v21, v20
	v_div_fmas_f32 v18, v18, v19, v21
	v_div_fixup_f32 v13, v18, v13, v5
	v_div_scale_f32 v5, s[4:5], v12, v12, v11
	v_rcp_f32_e32 v18, v5
	s_nop 0
	v_fma_f32 v19, -v5, v18, 1.0
	v_fmac_f32_e32 v18, v19, v18
	v_div_scale_f32 v19, vcc, v11, v12, v11
	v_mul_f32_e32 v20, v19, v18
	v_fma_f32 v21, -v5, v20, v19
	v_fmac_f32_e32 v20, v21, v18
	v_fma_f32 v5, -v5, v20, v19
	v_div_fmas_f32 v5, v5, v18, v20
	v_div_fixup_f32 v12, v5, v12, v11
	v_pk_mul_f32 v[12:13], v[14:15], v[12:13]
	s_nop 0
	v_cvt_pk_bf16_f32 v11, v12, v13
	global_store_dwordx2 v[0:1], v[10:11], off
	s_nop 0
	s_nop 0
	s_nop 0
	s_waitcnt lgkmcnt(0)
	v_mov_b32_e32 v14, v214
	v_mov_b32_e32 v15, v215
	v_mov_b32_e32 v10, v240
	v_mov_b32_e32 v11, v241
	v_mov_b32_e32 v12, v242
	v_mov_b32_e32 v13, v243
	v_and_b32_e32 v5, 0xffff0000, v14
	v_lshlrev_b32_e32 v14, 16, v14
	v_pk_mul_f32 v[16:17], v[16:17], v[4:5] op_sel_hi:[1,0]
	v_mul_f32_e32 v18, 0xbfb8aa3b, v14
	v_pk_mul_f32 v[10:11], v[16:17], v[10:11]
	v_mul_f32_e32 v16, 0xbfb8aa3b, v5
	v_exp_f32_e32 v18, v18
	v_exp_f32_e32 v19, v16
	s_nop 0
	v_pk_add_f32 v[16:17], v[18:19], 1.0 op_sel_hi:[1,0]
	s_nop 0
	v_div_scale_f32 v18, s[4:5], v17, v17, v5
	v_rcp_f32_e32 v19, v18
	s_nop 0
	v_fma_f32 v20, -v18, v19, 1.0
	v_fmac_f32_e32 v19, v20, v19
	v_div_scale_f32 v20, vcc, v5, v17, v5
	v_mul_f32_e32 v21, v20, v19
	v_fma_f32 v22, -v18, v21, v20
	v_fmac_f32_e32 v21, v22, v19
	v_fma_f32 v18, -v18, v21, v20
	v_div_fmas_f32 v18, v18, v19, v21
	v_div_fixup_f32 v17, v18, v17, v5
	v_div_scale_f32 v5, s[4:5], v16, v16, v14
	v_rcp_f32_e32 v18, v5
	s_nop 0
	v_fma_f32 v19, -v5, v18, 1.0
	v_fmac_f32_e32 v18, v19, v18
	v_div_scale_f32 v19, vcc, v14, v16, v14
	v_mul_f32_e32 v20, v19, v18
	v_fma_f32 v21, -v5, v20, v19
	v_fmac_f32_e32 v20, v21, v18
	v_fma_f32 v5, -v5, v20, v19
	v_div_fmas_f32 v5, v5, v18, v20
	v_div_fixup_f32 v16, v5, v16, v14
	v_pk_mul_f32 v[10:11], v[10:11], v[16:17]
	v_and_b32_e32 v5, 0xffff0000, v15
	v_cvt_pk_bf16_f32 v10, v10, v11
	v_lshlrev_b32_e32 v11, 16, v15
	v_pk_mul_f32 v[6:7], v[6:7], v[4:5] op_sel_hi:[1,0]
	v_mul_f32_e32 v14, 0xbfb8aa3b, v11
	v_pk_mul_f32 v[6:7], v[6:7], v[12:13]
	v_mul_f32_e32 v12, 0xbfb8aa3b, v5
	v_exp_f32_e32 v14, v14
	v_exp_f32_e32 v15, v12
	s_nop 0
	v_pk_add_f32 v[12:13], v[14:15], 1.0 op_sel_hi:[1,0]
	s_nop 0
	v_div_scale_f32 v14, s[4:5], v13, v13, v5
	v_rcp_f32_e32 v15, v14
	s_nop 0
	v_fma_f32 v16, -v14, v15, 1.0
	v_fmac_f32_e32 v15, v16, v15
	v_div_scale_f32 v16, vcc, v5, v13, v5
	v_mul_f32_e32 v17, v16, v15
	v_fma_f32 v18, -v14, v17, v16
	v_fmac_f32_e32 v17, v18, v15
	v_fma_f32 v14, -v14, v17, v16
	v_div_fmas_f32 v14, v14, v15, v17
	v_div_fixup_f32 v13, v14, v13, v5
	v_div_scale_f32 v5, s[4:5], v12, v12, v11
	v_rcp_f32_e32 v14, v5
	s_nop 0
	v_fma_f32 v15, -v5, v14, 1.0
	v_fmac_f32_e32 v14, v15, v14
	v_div_scale_f32 v15, vcc, v11, v12, v11
	v_mul_f32_e32 v16, v15, v14
	v_fma_f32 v17, -v5, v16, v15
	v_fmac_f32_e32 v16, v17, v14
	v_fma_f32 v5, -v5, v16, v15
	v_div_fmas_f32 v5, v5, v14, v16
	v_div_fixup_f32 v12, v5, v12, v11
	v_pk_mul_f32 v[6:7], v[6:7], v[12:13]
	s_nop 0
	v_cvt_pk_bf16_f32 v11, v6, v7
	global_store_dwordx2 v[0:1], v[10:11], off offset:16
	s_nop 0
	s_nop 0
	s_nop 0
	s_waitcnt lgkmcnt(0)
; DI size_t kblk(int row, int col, int nrows) { return ((size_t)(col >> 5) * nrows + row) * 32 + (col & 31); }
; DI float bf2f(bf16_t v) { return __uint_as_float(((unsigned)v) << 16); }
; DI unsigned pk2(float a, float b) { hwf32x2 f = {a, b}; hwbf16x2 r = __builtin_convertvector(f, hwbf16x2); return __builtin_bit_cast(unsigned, r); }
; DI float siluf_(float z) { return z / (1.f + __expf(-z)); }
; template <int MODE>
; DI void attn_mfma(const Params& p, int l, int b, int hd, int qb, unsigned char* smem) {
;     ...
;         for (int g4 = 0; g4 < 4; ++g4) {
;           const int v0 = vt * 32 + 8 * g4 + 4 * h2;
;           const ushort4 gt = *(const ushort4*)(P + qrow * PW + GATE + hd * 64 + v0);
;           const float4 gg = *(const float4*)(p.diff_g + l * 64 + v0);
;           uint2 o;
;           o.x = pk2(O[vt][4 * g4 + 0] * rstd * gg.x * siluf_(bf2f(gt.x)), O[vt][4 * g4 + 1] * rstd * gg.y * siluf_(bf2f(gt.y)));
;           o.y = pk2(O[vt][4 * g4 + 2] * rstd * gg.z * siluf_(bf2f(gt.z)), O[vt][4 * g4 + 3] * rstd * gg.w * siluf_(bf2f(gt.w)));
;           *(uint2*)(MIX + kblk((int)qrow, hd * 64 + v0, ROWS)) = o;
;         }
	v_mov_b32_e32 v6, v216
	v_mov_b32_e32 v7, v217
	v_mov_b32_e32 v10, v244
	v_mov_b32_e32 v11, v245
	v_mov_b32_e32 v12, v246
	v_mov_b32_e32 v13, v247
	v_and_b32_e32 v5, 0xffff0000, v6
	v_lshlrev_b32_e32 v6, 16, v6
	v_pk_mul_f32 v[8:9], v[8:9], v[4:5] op_sel_hi:[1,0]
	v_mul_f32_e32 v14, 0xbfb8aa3b, v6
	v_pk_mul_f32 v[8:9], v[8:9], v[10:11]
	v_mul_f32_e32 v10, 0xbfb8aa3b, v5
	v_exp_f32_e32 v14, v14
	v_exp_f32_e32 v15, v10
	s_nop 0
	v_pk_add_f32 v[10:11], v[14:15], 1.0 op_sel_hi:[1,0]
	s_nop 0
	v_div_scale_f32 v14, s[4:5], v11, v11, v5
	v_rcp_f32_e32 v15, v14
	s_nop 0
	v_fma_f32 v16, -v14, v15, 1.0
	v_fmac_f32_e32 v15, v16, v15
	v_div_scale_f32 v16, vcc, v5, v11, v5
	v_mul_f32_e32 v17, v16, v15
	v_fma_f32 v18, -v14, v17, v16
	v_fmac_f32_e32 v17, v18, v15
	v_fma_f32 v14, -v14, v17, v16
	v_div_fmas_f32 v14, v14, v15, v17
	v_div_fixup_f32 v11, v14, v11, v5
	v_div_scale_f32 v5, s[4:5], v10, v10, v6
	v_rcp_f32_e32 v14, v5
	s_nop 0
	v_fma_f32 v15, -v5, v14, 1.0
	v_fmac_f32_e32 v14, v15, v14
	v_div_scale_f32 v15, vcc, v6, v10, v6
	v_mul_f32_e32 v16, v15, v14
	v_fma_f32 v17, -v5, v16, v15
	v_fmac_f32_e32 v16, v17, v14
	v_fma_f32 v5, -v5, v16, v15
	v_div_fmas_f32 v5, v5, v14, v16
	v_div_fixup_f32 v10, v5, v10, v6
	v_pk_mul_f32 v[8:9], v[8:9], v[10:11]
	v_and_b32_e32 v5, 0xffff0000, v7
	v_lshlrev_b32_e32 v7, 16, v7
	v_cvt_pk_bf16_f32 v6, v8, v9
	v_mul_f32_e32 v8, 0xbfb8aa3b, v7
	v_mul_f32_e32 v9, 0xbfb8aa3b, v5
	v_exp_f32_e32 v8, v8
	v_exp_f32_e32 v9, v9
	v_pk_mul_f32 v[2:3], v[2:3], v[4:5] op_sel_hi:[1,0]
	v_pk_add_f32 v[8:9], v[8:9], 1.0 op_sel_hi:[1,0]
	s_nop 0
	v_div_scale_f32 v10, s[4:5], v9, v9, v5
	v_rcp_f32_e32 v11, v10
	v_pk_mul_f32 v[2:3], v[2:3], v[12:13]
	v_fma_f32 v12, -v10, v11, 1.0
	v_fmac_f32_e32 v11, v12, v11
	v_div_scale_f32 v12, vcc, v5, v9, v5
	v_mul_f32_e32 v13, v12, v11
	v_fma_f32 v14, -v10, v13, v12
	v_fmac_f32_e32 v13, v14, v11
	v_fma_f32 v10, -v10, v13, v12
	v_div_fmas_f32 v10, v10, v11, v13
	v_div_fixup_f32 v9, v10, v9, v5
	v_div_scale_f32 v5, s[4:5], v8, v8, v7
	v_rcp_f32_e32 v10, v5
	s_nop 0
	v_fma_f32 v11, -v5, v10, 1.0
	v_fmac_f32_e32 v10, v11, v10
	v_div_scale_f32 v11, vcc, v7, v8, v7
	v_mul_f32_e32 v12, v11, v10
	v_fma_f32 v13, -v5, v12, v11
	v_fmac_f32_e32 v12, v13, v10
	v_fma_f32 v5, -v5, v12, v11
	v_div_fmas_f32 v5, v5, v10, v12
	v_div_fixup_f32 v8, v5, v8, v7
	v_pk_mul_f32 v[2:3], v[2:3], v[8:9]
	s_nop 0
	v_cvt_pk_bf16_f32 v7, v2, v3
	global_store_dwordx2 v[0:1], v[6:7], off offset:32
	s_nop 0
	s_nop 0
	s_nop 0
	s_waitcnt lgkmcnt(0)
	v_mov_b32_e32 v2, v218
	v_mov_b32_e32 v3, v219
	v_mov_b32_e32 v6, v248
	v_mov_b32_e32 v7, v249
	v_mov_b32_e32 v8, v250
	v_mov_b32_e32 v9, v251
	v_and_b32_e32 v5, 0xffff0000, v2
	v_lshlrev_b32_e32 v2, 16, v2
	v_mul_f32_e32 v10, 0xbfb8aa3b, v2
	v_mul_f32_e32 v11, 0xbfb8aa3b, v5
	v_exp_f32_e32 v10, v10
	v_exp_f32_e32 v11, v11
	v_pk_mul_f32 v[12:13], v[34:35], v[4:5] op_sel_hi:[1,0]
	v_pk_add_f32 v[10:11], v[10:11], 1.0 op_sel_hi:[1,0]
	v_pk_mul_f32 v[6:7], v[12:13], v[6:7]
	v_div_scale_f32 v12, s[4:5], v11, v11, v5
	v_rcp_f32_e32 v13, v12
	s_nop 0
	v_fma_f32 v14, -v12, v13, 1.0
	v_fmac_f32_e32 v13, v14, v13
	v_div_scale_f32 v14, vcc, v5, v11, v5
	v_mul_f32_e32 v15, v14, v13
	v_fma_f32 v16, -v12, v15, v14
	v_fmac_f32_e32 v15, v16, v13
	v_fma_f32 v12, -v12, v15, v14
	v_div_fmas_f32 v12, v12, v13, v15
	v_div_fixup_f32 v11, v12, v11, v5
	v_div_scale_f32 v5, s[4:5], v10, v10, v2
	v_rcp_f32_e32 v12, v5
	s_nop 0
	v_fma_f32 v13, -v5, v12, 1.0
	v_fmac_f32_e32 v12, v13, v12
	v_div_scale_f32 v13, vcc, v2, v10, v2
	v_mul_f32_e32 v14, v13, v12
	v_fma_f32 v15, -v5, v14, v13
	v_fmac_f32_e32 v14, v15, v12
	v_fma_f32 v5, -v5, v14, v13
	v_div_fmas_f32 v5, v5, v12, v14
	v_div_fixup_f32 v10, v5, v10, v2
	v_pk_mul_f32 v[6:7], v[6:7], v[10:11]
	v_and_b32_e32 v10, 0xffff0000, v3
	v_lshlrev_b32_e32 v3, 16, v3
	v_cvt_pk_bf16_f32 v2, v6, v7
	v_mul_f32_e32 v5, 0xbfb8aa3b, v3
	v_mul_f32_e32 v7, 0xbfb8aa3b, v10
	v_exp_f32_e32 v6, v5
	v_exp_f32_e32 v7, v7
	v_pk_mul_f32 v[4:5], v[32:33], v[4:5] op_sel_hi:[1,0]
	v_pk_add_f32 v[6:7], v[6:7], 1.0 op_sel_hi:[1,0]
	v_pk_mul_f32 v[4:5], v[4:5], v[8:9]
	v_div_scale_f32 v8, s[4:5], v7, v7, v10
	v_rcp_f32_e32 v9, v8
	s_nop 0
	v_fma_f32 v11, -v8, v9, 1.0
	v_fmac_f32_e32 v9, v11, v9
	v_div_scale_f32 v11, vcc, v10, v7, v10
	v_mul_f32_e32 v12, v11, v9
	v_fma_f32 v13, -v8, v12, v11
	v_fmac_f32_e32 v12, v13, v9
	v_fma_f32 v8, -v8, v12, v11
	v_div_fmas_f32 v8, v8, v9, v12
	v_div_fixup_f32 v7, v8, v7, v10
	v_div_scale_f32 v8, s[4:5], v6, v6, v3
	v_rcp_f32_e32 v9, v8
	s_nop 0
	v_fma_f32 v10, -v8, v9, 1.0
	v_fmac_f32_e32 v9, v10, v9
	v_div_scale_f32 v10, vcc, v3, v6, v3
	v_mul_f32_e32 v11, v10, v9
	v_fma_f32 v12, -v8, v11, v10
	v_fmac_f32_e32 v11, v12, v9
	v_fma_f32 v8, -v8, v11, v10
	v_div_fmas_f32 v8, v8, v9, v11
	v_div_fixup_f32 v6, v8, v6, v3
	v_pk_mul_f32 v[4:5], v[4:5], v[6:7]
	s_nop 0
	v_cvt_pk_bf16_f32 v3, v4, v5
	global_store_dwordx2 v[0:1], v[2:3], off offset:48

; template <int MX>
; DI RecRaw rec_load(const Params& p, int b, int h, int dir, int T0, int tid) {
;   const bf16_t* P = (const bf16_t*)(p.ws + WS_P);
;   const int tt = tid >> 2, k0 = (tid & 3) * 16;
;   const size_t row = (size_t)b * NTOK + T0 + tt;
;   const bf16_t* rp = P + row * PW;
;   RecRaw w;
;   if (MX == 0) {
;     const int fcol = (dir ? B_FB : B_FF) + h * 64 + k0;
;     w.a0 = *(const uint4*)(rp + fcol); w.a1 = *(const uint4*)(rp + fcol + 8);
;     w.b0 = *(const uint4*)(rp + B_Q + h * 64 + k0); w.b1 = *(const uint4*)(rp + B_Q + h * 64 + k0 + 8);
;     w.c0 = *(const uint4*)(rp + B_I + h * 64 + k0); w.c1 = *(const uint4*)(rp + B_I + h * 64 + k0 + 8);
;     w.ig = 0.f; w.fg = 0.f;
;   } else {
;     w.a0 = *(const uint4*)(rp + D_K + h * 64 + k0); w.a1 = *(const uint4*)(rp + D_K + h * 64 + k0 + 8);
;     w.b0 = *(const uint4*)(rp + D_Q + h * 64 + k0); w.b1 = *(const uint4*)(rp + D_Q + h * 64 + k0 + 8);
;     w.c0 = *(const uint4*)(rp + D_V + h * 64 + k0); w.c1 = *(const uint4*)(rp + D_V + h * 64 + k0 + 8);
;     const float* G = (const float*)(p.ws + WS_GATES) + row * 16;
;     w.ig = G[dir * 4 + h]; w.fg = G[8 + dir * 4 + h];
;   }
;   return w;
; }
; template <int MX>
; DI void rec_output(const Params& p, int l, int b, int h, int sc, unsigned char* smem) {
;     ...
; #pragma unroll 1
;     for (int ci = 0; ci < 4; ++ci) {
;       const int c = dir == 0 ? ci : 3 - ci;
;       const int cn = dir == 0 ? (ci < 3 ? ci + 1 : ci) : (ci < 3 ? 2 - ci : 0);
;       const RecRaw nxt = rec_load<MX>(p, b, h, dir, sc * 256 + cn * 64, tid);
;       rec_chunk<MX, true>(p, l, b, h, dir, sc * 256 + c * 64, smem, St, nst, dtot, tid, raw);
;       raw = nxt;
;     }
.LBB0_600:
	s_or_b64 exec, exec, s[0:1]
	s_add_i32 s52, s52, -1
	s_add_i32 s13, s13, 1
	s_cmp_eq_u32 s52, -2
	s_waitcnt vmcnt(0)
	v_mov_b32_e32 v64, v235
	v_mov_b32_e32 v65, v236
	v_mov_b64_e32 v[56:57], v[32:33]
	v_mov_b64_e32 v[58:59], v[34:35]
	v_mov_b64_e32 v[48:49], v[12:13]
	v_mov_b64_e32 v[50:51], v[14:15]
	v_mov_b64_e32 v[40:41], v[8:9]
	v_mov_b64_e32 v[42:43], v[10:11]
	v_mov_b64_e32 v[44:45], v[28:29]
	v_mov_b64_e32 v[46:47], v[30:31]
	v_mov_b64_e32 v[60:61], v[16:17]
	v_mov_b64_e32 v[62:63], v[18:19]
	v_mov_b64_e32 v[52:53], v[20:21]
	v_mov_b64_e32 v[54:55], v[22:23]
	s_cbranch_scc1 .LBB0_596
.LBB0_601:
	v_add_co_u32_e64 v91, s[0:1], s52, 1
	s_and_b64 s[0:1], s[0:1], exec
	s_cselect_b32 s21, 3, s13
	s_cselect_b32 s46, 0, s52
	s_and_b64 s[0:1], s[24:25], exec
	s_cselect_b32 s0, s21, s46
	s_lshl_b32 s0, s0, 6
	s_ashr_i32 s1, s0, 31
	v_lshl_add_u64 v[66:67], v[80:81], 0, s[0:1]
	v_mov_b64_e32 v[8:9], s[18:19]
	v_mad_u64_u32 v[8:9], s[0:1], v66, s33, v[8:9]
	v_mad_i32_i24 v9, v67, s33, v9
	v_lshl_add_u64 v[8:9], v[8:9], 0, s[34:35]
	v_lshl_add_u64 v[16:17], v[8:9], 0, v[94:95]
	s_mov_b64 s[0:1], 0x1400
	v_lshl_add_u64 v[8:9], v[16:17], 0, s[0:1]
	s_mov_b64 s[0:1], 0x1200
	v_add_co_u32_e32 v18, vcc, s16, v16
	v_lshl_add_u64 v[20:21], v[16:17], 0, s[0:1]
	s_mov_b64 s[0:1], 0x1600
	v_addc_co_u32_e32 v19, vcc, 0, v17, vcc
	v_lshl_add_u64 v[22:23], v[16:17], 0, s[0:1]
	global_load_dwordx4 v[12:15], v[8:9], off offset:16
	s_nop 0
	global_load_dwordx4 v[8:11], v[18:19], off offset:512
	global_load_dwordx4 v[32:35], v[18:19], off offset:1024
	s_nop 0
	global_load_dwordx4 v[16:19], v[18:19], off offset:1536
	s_nop 0
	global_load_dwordx4 v[28:31], v[20:21], off offset:16
	s_nop 0
	global_load_dwordx4 v[20:23], v[22:23], off offset:16
	v_lshlrev_b64 v[66:67], 6, v[66:67]
	v_lshl_add_u64 v[66:67], s[26:27], 0, v[66:67]
	global_load_dword v235, v[66:67], off
	global_load_dword v236, v[66:67], off offset:32
	s_mov_b32 s0, 0xc1a00000
	s_waitcnt vmcnt(8) lgkmcnt(0)
	v_cmp_ngt_f32_e32 vcc, s0, v65
	s_and_saveexec_b64 s[0:1], vcc
	s_xor_b64 s[0:1], exec, s[0:1]
	s_cbranch_execz .LBB0_691
	v_mul_f32_e32 v65, 0xbfb8aa3b, v65
	v_exp_f32_e32 v65, v65
	s_nop 0
	v_add_f32_e32 v65, 1.0, v65
	v_log_f32_e32 v65, v65
	s_nop 0
	v_xor_b32_e32 v66, 0x80000000, v65
	s_andn2_saveexec_b64 s[0:1], s[0:1]
	s_cbranch_execnz .LBB0_692

; DI size_t kblk(int row, int col, int nrows) { return ((size_t)(col >> 5) * nrows + row) * 32 + (col & 31); }
; DI float bf2f(bf16_t v) { return __uint_as_float(((unsigned)v) << 16); }
; DI unsigned pk2(float a, float b) { hwf32x2 f = {a, b}; hwbf16x2 r = __builtin_convertvector(f, hwbf16x2); return __builtin_bit_cast(unsigned, r); }
; DI float siluf_(float z) { return z / (1.f + __expf(-z)); }
; template <int MODE>
; DI void attn_mfma(const Params& p, int l, int b, int hd, int qb, unsigned char* smem) {
;     ...
;     const float i0 = 1.f / ltot;
; #pragma unroll
;     for (int vt = 0; vt < 2; ++vt)
; #pragma unroll
;       for (int g4 = 0; g4 < 4; ++g4) {
;         const int v0 = vt * 32 + 8 * g4 + 4 * h2;
;         const ushort4 gt = *(const ushort4*)(P + qrow * PW + GATE + 512 + hd * 64 + v0);
;         uint2 o;
;         o.x = pk2(O[vt][4 * g4 + 0] * i0 * siluf_(bf2f(gt.x)), O[vt][4 * g4 + 1] * i0 * siluf_(bf2f(gt.y)));
;         o.y = pk2(O[vt][4 * g4 + 2] * i0 * siluf_(bf2f(gt.z)), O[vt][4 * g4 + 3] * i0 * siluf_(bf2f(gt.w)));
;         *(uint2*)(MIX + kblk((int)qrow, 512 + hd * 64 + v0, ROWS)) = o;
;       }
.LBB0_829:
	v_cmp_lt_i32_e32 vcc, v33, v34
	s_add_u32 s0, s14, 0x1dc6000
	s_addc_u32 s1, s15, 0
	v_cndmask_b32_e32 v32, v32, v33, vcc
	v_lshlrev_b32_e32 v32, 2, v32
	ds_bpermute_b32 v32, v32, v200
	s_lshl_b32 s2, s11, 1
	v_ashrrev_i32_e32 v145, 31, v144
	v_mov_b32_e32 v153, v161
	v_lshlrev_b64 v[38:39], 1, v[152:153]
	s_waitcnt lgkmcnt(0)
	v_add_f32_e32 v32, v200, v32
	v_div_scale_f32 v33, s[4:5], v32, v32, 1.0
	v_rcp_f32_e32 v34, v33
	s_mov_b64 s[4:5], 0x1e20
	v_mov_b32_e32 v151, v161
	v_mov_b32_e32 v149, v161
	v_fma_f32 v35, -v33, v34, 1.0
	v_fmac_f32_e32 v34, v35, v34
	v_div_scale_f32 v35, vcc, 1.0, v32, 1.0
	v_mul_f32_e32 v36, v35, v34
	v_fma_f32 v37, -v33, v36, v35
	v_fmac_f32_e32 v36, v37, v34
	v_fma_f32 v33, -v33, v36, v35
	v_div_fmas_f32 v33, v33, v34, v36
	v_lshl_add_u64 v[34:35], v[154:155], 0, s[2:3]
	v_lshl_add_u64 v[42:43], v[34:35], 0, s[4:5]
	s_mul_i32 s4, s10, 0x9000
	s_add_i32 s2, s4, 0x48000
	v_lshl_add_u64 v[34:35], v[144:145], 0, s[2:3]
	v_lshlrev_b64 v[34:35], 6, v[34:35]
	v_lshl_add_u64 v[40:41], s[0:1], 0, v[34:35]
	v_lshl_add_u64 v[34:35], v[42:43], 0, v[38:39]
	global_load_dwordx2 v[204:205], v[34:35], off
	global_load_dwordx2 v[206:207], v[34:35], off offset:16
	global_load_dwordx2 v[208:209], v[34:35], off offset:32
	global_load_dwordx2 v[210:211], v[34:35], off offset:48
	global_load_dwordx2 v[212:213], v[34:35], off offset:64
	global_load_dwordx2 v[214:215], v[34:35], off offset:80
	global_load_dwordx2 v[216:217], v[34:35], off offset:96
	global_load_dwordx2 v[218:219], v[34:35], off offset:112
	s_nop 0
	v_div_fixup_f32 v32, v33, v32, 1.0
	v_mov_b32_e32 v147, v161
	s_add_i32 s2, s4, 0x4c800
	s_waitcnt vmcnt(0) lgkmcnt(0)
	v_mov_b32_e32 v36, v204
	v_mov_b32_e32 v37, v205
	v_and_b32_e32 v33, 0xffff0000, v36
	v_lshlrev_b32_e32 v36, 16, v36
	v_mul_f32_e32 v44, 0xbfb8aa3b, v36
	v_mul_f32_e32 v45, 0xbfb8aa3b, v33
	v_exp_f32_e32 v44, v44
	v_exp_f32_e32 v45, v45
	v_pk_mul_f32 v[16:17], v[16:17], v[32:33] op_sel_hi:[1,0]
	v_pk_add_f32 v[44:45], v[44:45], 1.0 op_sel_hi:[1,0]
	s_nop 0
	v_div_scale_f32 v46, s[6:7], v45, v45, v33
	v_rcp_f32_e32 v47, v46
	s_nop 0
	v_fma_f32 v48, -v46, v47, 1.0
	v_fmac_f32_e32 v47, v48, v47
	v_div_scale_f32 v48, vcc, v33, v45, v33
	v_mul_f32_e32 v49, v48, v47
	v_fma_f32 v50, -v46, v49, v48
	v_fmac_f32_e32 v49, v50, v47
	v_fma_f32 v46, -v46, v49, v48
	v_div_fmas_f32 v46, v46, v47, v49
	v_div_fixup_f32 v45, v46, v45, v33
	v_div_scale_f32 v33, s[6:7], v44, v44, v36
	v_rcp_f32_e32 v46, v33
	s_nop 0
	v_fma_f32 v47, -v33, v46, 1.0
	v_fmac_f32_e32 v46, v47, v46
	v_div_scale_f32 v47, vcc, v36, v44, v36
	v_mul_f32_e32 v48, v47, v46
	v_fma_f32 v49, -v33, v48, v47
	v_fmac_f32_e32 v48, v49, v46
	v_fma_f32 v33, -v33, v48, v47
	v_div_fmas_f32 v33, v33, v46, v48
	v_div_fixup_f32 v44, v33, v44, v36
	v_pk_mul_f32 v[16:17], v[16:17], v[44:45]
	v_lshlrev_b32_e32 v33, 16, v37
	v_cvt_pk_bf16_f32 v16, v16, v17
	v_and_b32_e32 v17, 0xffff0000, v37
	v_mul_f32_e32 v36, 0xbfb8aa3b, v33
	v_mul_f32_e32 v37, 0xbfb8aa3b, v17
	v_exp_f32_e32 v36, v36
	v_exp_f32_e32 v37, v37
	v_pk_mul_f32 v[18:19], v[18:19], v[32:33] op_sel_hi:[1,0]
	v_pk_add_f32 v[36:37], v[36:37], 1.0 op_sel_hi:[1,0]
	s_nop 0
	v_div_scale_f32 v44, s[6:7], v37, v37, v17
	v_rcp_f32_e32 v45, v44
	s_nop 0
	v_fma_f32 v46, -v44, v45, 1.0
	v_fmac_f32_e32 v45, v46, v45
	v_div_scale_f32 v46, vcc, v17, v37, v17
	v_mul_f32_e32 v47, v46, v45
	v_fma_f32 v48, -v44, v47, v46
	v_fmac_f32_e32 v47, v48, v45
	v_fma_f32 v44, -v44, v47, v46
	v_div_fmas_f32 v44, v44, v45, v47
	v_div_fixup_f32 v37, v44, v37, v17
	v_div_scale_f32 v17, s[6:7], v36, v36, v33
	v_rcp_f32_e32 v44, v17
	s_nop 0
	v_fma_f32 v45, -v17, v44, 1.0
	v_fmac_f32_e32 v44, v45, v44
	v_div_scale_f32 v45, vcc, v33, v36, v33
	v_mul_f32_e32 v46, v45, v44
	v_fma_f32 v47, -v17, v46, v45
	v_fmac_f32_e32 v46, v47, v44
	v_fma_f32 v17, -v17, v46, v45
	v_div_fmas_f32 v17, v17, v44, v46
	v_div_fixup_f32 v36, v17, v36, v33
	v_pk_mul_f32 v[18:19], v[18:19], v[36:37]
	v_lshlrev_b64 v[36:37], 1, v[150:151]
	v_cvt_pk_bf16_f32 v17, v18, v19
	v_lshl_add_u64 v[18:19], v[40:41], 0, v[38:39]
	global_store_dwordx2 v[18:19], v[16:17], off
	v_lshl_add_u64 v[16:17], v[42:43], 0, v[36:37]
	s_nop 0
	s_waitcnt lgkmcnt(0)
	v_mov_b32_e32 v16, v206
	v_mov_b32_e32 v17, v207
	v_and_b32_e32 v33, 0xffff0000, v16
	v_lshlrev_b32_e32 v16, 16, v16
	v_mul_f32_e32 v18, 0xbfb8aa3b, v16
	v_mul_f32_e32 v19, 0xbfb8aa3b, v33
	v_exp_f32_e32 v18, v18
	v_exp_f32_e32 v19, v19
	v_pk_mul_f32 v[20:21], v[20:21], v[32:33] op_sel_hi:[1,0]
	v_pk_add_f32 v[18:19], v[18:19], 1.0 op_sel_hi:[1,0]
	s_nop 0
	v_div_scale_f32 v44, s[6:7], v19, v19, v33
	v_rcp_f32_e32 v45, v44
	s_nop 0
	v_fma_f32 v46, -v44, v45, 1.0
	v_fmac_f32_e32 v45, v46, v45
	v_div_scale_f32 v46, vcc, v33, v19, v33
	v_mul_f32_e32 v47, v46, v45
	v_fma_f32 v48, -v44, v47, v46
	v_fmac_f32_e32 v47, v48, v45
	v_fma_f32 v44, -v44, v47, v46
	v_div_fmas_f32 v44, v44, v45, v47
	v_div_fixup_f32 v19, v44, v19, v33
	v_div_scale_f32 v33, s[6:7], v18, v18, v16
	v_rcp_f32_e32 v44, v33
	s_nop 0
	v_fma_f32 v45, -v33, v44, 1.0
	v_fmac_f32_e32 v44, v45, v44
	v_div_scale_f32 v45, vcc, v16, v18, v16
	v_mul_f32_e32 v46, v45, v44
	v_fma_f32 v47, -v33, v46, v45
	v_fmac_f32_e32 v46, v47, v44
	v_fma_f32 v33, -v33, v46, v45
	v_div_fmas_f32 v33, v33, v44, v46
	v_div_fixup_f32 v18, v33, v18, v16
	v_pk_mul_f32 v[18:19], v[20:21], v[18:19]
	v_and_b32_e32 v33, 0xffff0000, v17
	v_lshlrev_b32_e32 v17, 16, v17
	v_cvt_pk_bf16_f32 v16, v18, v19
	v_mul_f32_e32 v18, 0xbfb8aa3b, v17
	v_mul_f32_e32 v19, 0xbfb8aa3b, v33
	v_exp_f32_e32 v18, v18
	v_exp_f32_e32 v19, v19
	v_pk_mul_f32 v[20:21], v[22:23], v[32:33] op_sel_hi:[1,0]
	v_pk_add_f32 v[18:19], v[18:19], 1.0 op_sel_hi:[1,0]
	s_nop 0
	v_div_scale_f32 v22, s[6:7], v19, v19, v33
	v_rcp_f32_e32 v23, v22
	s_nop 0
	v_fma_f32 v44, -v22, v23, 1.0
	v_fmac_f32_e32 v23, v44, v23
	v_div_scale_f32 v44, vcc, v33, v19, v33
	v_mul_f32_e32 v45, v44, v23
	v_fma_f32 v46, -v22, v45, v44
	v_fmac_f32_e32 v45, v46, v23
	v_fma_f32 v22, -v22, v45, v44
	v_div_fmas_f32 v22, v22, v23, v45
	v_div_fixup_f32 v19, v22, v19, v33
	v_div_scale_f32 v22, s[6:7], v18, v18, v17
	v_rcp_f32_e32 v23, v22
	s_nop 0
	v_fma_f32 v33, -v22, v23, 1.0
	v_fmac_f32_e32 v23, v33, v23
	v_div_scale_f32 v33, vcc, v17, v18, v17
	v_mul_f32_e32 v44, v33, v23
	v_fma_f32 v45, -v22, v44, v33
	v_fmac_f32_e32 v44, v45, v23
	v_fma_f32 v22, -v22, v44, v33
	v_div_fmas_f32 v22, v22, v23, v44
	v_div_fixup_f32 v18, v22, v18, v17
	v_pk_mul_f32 v[18:19], v[20:21], v[18:19]
	s_nop 0
	v_cvt_pk_bf16_f32 v17, v18, v19
	v_lshl_add_u64 v[18:19], v[40:41], 0, v[36:37]
	global_store_dwordx2 v[18:19], v[16:17], off
	v_lshlrev_b64 v[18:19], 1, v[148:149]
	v_lshl_add_u64 v[16:17], v[42:43], 0, v[18:19]
	s_nop 0
	s_waitcnt lgkmcnt(0)
; DI size_t kblk(int row, int col, int nrows) { return ((size_t)(col >> 5) * nrows + row) * 32 + (col & 31); }
; DI float bf2f(bf16_t v) { return __uint_as_float(((unsigned)v) << 16); }
; DI unsigned pk2(float a, float b) { hwf32x2 f = {a, b}; hwbf16x2 r = __builtin_convertvector(f, hwbf16x2); return __builtin_bit_cast(unsigned, r); }
; DI float siluf_(float z) { return z / (1.f + __expf(-z)); }
; template <int MODE>
; DI void attn_mfma(const Params& p, int l, int b, int hd, int qb, unsigned char* smem) {
;     ...
;     const float i0 = 1.f / ltot;
; #pragma unroll
;     for (int vt = 0; vt < 2; ++vt)
; #pragma unroll
;       for (int g4 = 0; g4 < 4; ++g4) {
;         const int v0 = vt * 32 + 8 * g4 + 4 * h2;
;         const ushort4 gt = *(const ushort4*)(P + qrow * PW + GATE + 512 + hd * 64 + v0);
;         uint2 o;
;         o.x = pk2(O[vt][4 * g4 + 0] * i0 * siluf_(bf2f(gt.x)), O[vt][4 * g4 + 1] * i0 * siluf_(bf2f(gt.y)));
;         o.y = pk2(O[vt][4 * g4 + 2] * i0 * siluf_(bf2f(gt.z)), O[vt][4 * g4 + 3] * i0 * siluf_(bf2f(gt.w)));
;         *(uint2*)(MIX + kblk((int)qrow, 512 + hd * 64 + v0, ROWS)) = o;
;       }
	v_mov_b32_e32 v16, v208
	v_mov_b32_e32 v17, v209
	v_and_b32_e32 v33, 0xffff0000, v16
	v_lshlrev_b32_e32 v16, 16, v16
	v_mul_f32_e32 v20, 0xbfb8aa3b, v16
	v_mul_f32_e32 v21, 0xbfb8aa3b, v33
	v_exp_f32_e32 v20, v20
	v_exp_f32_e32 v21, v21
	v_pk_mul_f32 v[22:23], v[24:25], v[32:33] op_sel_hi:[1,0]
	v_pk_add_f32 v[20:21], v[20:21], 1.0 op_sel_hi:[1,0]
	s_nop 0
	v_div_scale_f32 v24, s[6:7], v21, v21, v33
	v_rcp_f32_e32 v25, v24
	s_nop 0
	v_fma_f32 v44, -v24, v25, 1.0
	v_fmac_f32_e32 v25, v44, v25
	v_div_scale_f32 v44, vcc, v33, v21, v33
	v_mul_f32_e32 v45, v44, v25
	v_fma_f32 v46, -v24, v45, v44
	v_fmac_f32_e32 v45, v46, v25
	v_fma_f32 v24, -v24, v45, v44
	v_div_fmas_f32 v24, v24, v25, v45
	v_div_fixup_f32 v21, v24, v21, v33
	v_div_scale_f32 v24, s[6:7], v20, v20, v16
	v_rcp_f32_e32 v25, v24
	s_nop 0
	v_fma_f32 v33, -v24, v25, 1.0
	v_fmac_f32_e32 v25, v33, v25
	v_div_scale_f32 v33, vcc, v16, v20, v16
	v_mul_f32_e32 v44, v33, v25
	v_fma_f32 v45, -v24, v44, v33
	v_fmac_f32_e32 v44, v45, v25
	v_fma_f32 v24, -v24, v44, v33
	v_div_fmas_f32 v24, v24, v25, v44
	v_div_fixup_f32 v20, v24, v20, v16
	v_pk_mul_f32 v[20:21], v[22:23], v[20:21]
	v_and_b32_e32 v24, 0xffff0000, v17
	v_lshlrev_b32_e32 v17, 16, v17
	v_cvt_pk_bf16_f32 v16, v20, v21
	v_mul_f32_e32 v20, 0xbfb8aa3b, v17
	v_mul_f32_e32 v21, 0xbfb8aa3b, v24
	v_exp_f32_e32 v20, v20
	v_exp_f32_e32 v21, v21
	v_pk_mul_f32 v[22:23], v[26:27], v[32:33] op_sel_hi:[1,0]
	v_pk_add_f32 v[20:21], v[20:21], 1.0 op_sel_hi:[1,0]
	s_nop 0
	v_div_scale_f32 v25, s[6:7], v21, v21, v24
	v_rcp_f32_e32 v26, v25
	s_nop 0
	v_fma_f32 v27, -v25, v26, 1.0
	v_fmac_f32_e32 v26, v27, v26
	v_div_scale_f32 v27, vcc, v24, v21, v24
	v_mul_f32_e32 v33, v27, v26
	v_fma_f32 v44, -v25, v33, v27
	v_fmac_f32_e32 v33, v44, v26
	v_fma_f32 v25, -v25, v33, v27
	v_div_fmas_f32 v25, v25, v26, v33
	v_div_fixup_f32 v21, v25, v21, v24
	v_div_scale_f32 v24, s[6:7], v20, v20, v17
	v_rcp_f32_e32 v25, v24
	s_nop 0
	v_fma_f32 v26, -v24, v25, 1.0
	v_fmac_f32_e32 v25, v26, v25
	v_div_scale_f32 v26, vcc, v17, v20, v17
	v_mul_f32_e32 v27, v26, v25
	v_fma_f32 v33, -v24, v27, v26
	v_fmac_f32_e32 v27, v33, v25
	v_fma_f32 v24, -v24, v27, v26
	v_div_fmas_f32 v24, v24, v25, v27
	v_div_fixup_f32 v20, v24, v20, v17
	v_pk_mul_f32 v[20:21], v[22:23], v[20:21]
	v_pk_mul_f32 v[24:25], v[28:29], v[32:33] op_sel_hi:[1,0]
	v_cvt_pk_bf16_f32 v17, v20, v21
	v_lshl_add_u64 v[20:21], v[40:41], 0, v[18:19]
	global_store_dwordx2 v[20:21], v[16:17], off
	v_lshlrev_b64 v[16:17], 1, v[146:147]
	v_lshl_add_u64 v[20:21], v[42:43], 0, v[16:17]
	s_nop 0
	s_waitcnt lgkmcnt(0)
	v_mov_b32_e32 v20, v210
	v_mov_b32_e32 v21, v211
	v_and_b32_e32 v26, 0xffff0000, v20
	v_lshlrev_b32_e32 v20, 16, v20
	v_mul_f32_e32 v22, 0xbfb8aa3b, v20
	v_mul_f32_e32 v23, 0xbfb8aa3b, v26
	v_exp_f32_e32 v22, v22
	v_exp_f32_e32 v23, v23
	s_nop 0
	v_pk_add_f32 v[22:23], v[22:23], 1.0 op_sel_hi:[1,0]
	s_nop 0
	v_div_scale_f32 v27, s[6:7], v23, v23, v26
	v_rcp_f32_e32 v28, v27
	s_nop 0
	v_fma_f32 v29, -v27, v28, 1.0
	v_fmac_f32_e32 v28, v29, v28
	v_div_scale_f32 v29, vcc, v26, v23, v26
	v_mul_f32_e32 v33, v29, v28
	v_fma_f32 v42, -v27, v33, v29
	v_fmac_f32_e32 v33, v42, v28
	v_fma_f32 v27, -v27, v33, v29
	v_div_fmas_f32 v27, v27, v28, v33
	v_div_fixup_f32 v23, v27, v23, v26
	v_div_scale_f32 v26, s[6:7], v22, v22, v20
	v_rcp_f32_e32 v27, v26
	s_nop 0
	v_fma_f32 v28, -v26, v27, 1.0
	v_fmac_f32_e32 v27, v28, v27
	v_div_scale_f32 v28, vcc, v20, v22, v20
	v_mul_f32_e32 v29, v28, v27
	v_fma_f32 v33, -v26, v29, v28
	v_fmac_f32_e32 v29, v33, v27
	v_fma_f32 v26, -v26, v29, v28
	v_div_fmas_f32 v26, v26, v27, v29
	v_div_fixup_f32 v22, v26, v22, v20
	v_pk_mul_f32 v[22:23], v[24:25], v[22:23]
	v_and_b32_e32 v26, 0xffff0000, v21
	v_lshlrev_b32_e32 v21, 16, v21
	v_cvt_pk_bf16_f32 v20, v22, v23
	v_mul_f32_e32 v22, 0xbfb8aa3b, v21
	v_mul_f32_e32 v23, 0xbfb8aa3b, v26
	v_exp_f32_e32 v22, v22
	v_exp_f32_e32 v23, v23
	v_pk_mul_f32 v[24:25], v[30:31], v[32:33] op_sel_hi:[1,0]
	v_pk_mul_f32 v[0:1], v[0:1], v[32:33] op_sel_hi:[1,0]
	v_pk_mul_f32 v[2:3], v[2:3], v[32:33] op_sel_hi:[1,0]
	v_pk_add_f32 v[22:23], v[22:23], 1.0 op_sel_hi:[1,0]
	v_pk_mul_f32 v[4:5], v[4:5], v[32:33] op_sel_hi:[1,0]
	v_div_scale_f32 v27, s[6:7], v23, v23, v26
	v_rcp_f32_e32 v28, v27
	s_nop 0
	v_fma_f32 v29, -v27, v28, 1.0
	v_fmac_f32_e32 v28, v29, v28
	v_div_scale_f32 v29, vcc, v26, v23, v26
	v_mul_f32_e32 v30, v29, v28
	v_fma_f32 v31, -v27, v30, v29
	v_fmac_f32_e32 v30, v31, v28
	v_fma_f32 v27, -v27, v30, v29
	v_div_fmas_f32 v27, v27, v28, v30
	v_div_fixup_f32 v23, v27, v23, v26
	v_div_scale_f32 v26, s[6:7], v22, v22, v21
	v_rcp_f32_e32 v27, v26
	s_nop 0
	v_fma_f32 v28, -v26, v27, 1.0
	v_fmac_f32_e32 v27, v28, v27
	v_div_scale_f32 v28, vcc, v21, v22, v21
	v_mul_f32_e32 v29, v28, v27
	v_fma_f32 v30, -v26, v29, v28
	v_fmac_f32_e32 v29, v30, v27
	v_fma_f32 v26, -v26, v29, v28
	v_div_fmas_f32 v26, v26, v27, v29
	v_div_fixup_f32 v22, v26, v22, v21
	v_pk_mul_f32 v[22:23], v[24:25], v[22:23]
	s_nop 0
	v_cvt_pk_bf16_f32 v21, v22, v23
	v_lshl_add_u64 v[22:23], v[40:41], 0, v[16:17]
	global_store_dwordx2 v[22:23], v[20:21], off
	s_nop 0
	v_lshl_add_u64 v[20:21], v[144:145], 0, s[2:3]
	v_lshlrev_b64 v[20:21], 6, v[20:21]
	v_lshl_add_u64 v[20:21], s[0:1], 0, v[20:21]
	s_waitcnt lgkmcnt(0)
; DI size_t kblk(int row, int col, int nrows) { return ((size_t)(col >> 5) * nrows + row) * 32 + (col & 31); }
; DI float bf2f(bf16_t v) { return __uint_as_float(((unsigned)v) << 16); }
; DI unsigned pk2(float a, float b) { hwf32x2 f = {a, b}; hwbf16x2 r = __builtin_convertvector(f, hwbf16x2); return __builtin_bit_cast(unsigned, r); }
; DI float siluf_(float z) { return z / (1.f + __expf(-z)); }
; template <int MODE>
; DI void attn_mfma(const Params& p, int l, int b, int hd, int qb, unsigned char* smem) {
;     ...
;     const float i0 = 1.f / ltot;
; #pragma unroll
;     for (int vt = 0; vt < 2; ++vt)
; #pragma unroll
;       for (int g4 = 0; g4 < 4; ++g4) {
;         const int v0 = vt * 32 + 8 * g4 + 4 * h2;
;         const ushort4 gt = *(const ushort4*)(P + qrow * PW + GATE + 512 + hd * 64 + v0);
;         uint2 o;
;         o.x = pk2(O[vt][4 * g4 + 0] * i0 * siluf_(bf2f(gt.x)), O[vt][4 * g4 + 1] * i0 * siluf_(bf2f(gt.y)));
;         o.y = pk2(O[vt][4 * g4 + 2] * i0 * siluf_(bf2f(gt.z)), O[vt][4 * g4 + 3] * i0 * siluf_(bf2f(gt.w)));
;         *(uint2*)(MIX + kblk((int)qrow, 512 + hd * 64 + v0, ROWS)) = o;
;       }
	v_mov_b32_e32 v22, v212
	v_mov_b32_e32 v23, v213
	v_and_b32_e32 v26, 0xffff0000, v22
	v_lshlrev_b32_e32 v22, 16, v22
	v_mul_f32_e32 v24, 0xbfb8aa3b, v22
	v_mul_f32_e32 v25, 0xbfb8aa3b, v26
	v_exp_f32_e32 v24, v24
	v_exp_f32_e32 v25, v25
	s_nop 0
	v_pk_add_f32 v[24:25], v[24:25], 1.0 op_sel_hi:[1,0]
	s_nop 0
	v_div_scale_f32 v27, s[0:1], v25, v25, v26
	v_rcp_f32_e32 v28, v27
	s_nop 0
	v_fma_f32 v29, -v27, v28, 1.0
	v_fmac_f32_e32 v28, v29, v28
	v_div_scale_f32 v29, vcc, v26, v25, v26
	v_mul_f32_e32 v30, v29, v28
	v_fma_f32 v31, -v27, v30, v29
	v_fmac_f32_e32 v30, v31, v28
	v_fma_f32 v27, -v27, v30, v29
	v_div_fmas_f32 v27, v27, v28, v30
	v_div_fixup_f32 v25, v27, v25, v26
	v_div_scale_f32 v26, s[0:1], v24, v24, v22
	v_rcp_f32_e32 v27, v26
	s_nop 0
	v_fma_f32 v28, -v26, v27, 1.0
	v_fmac_f32_e32 v27, v28, v27
	v_div_scale_f32 v28, vcc, v22, v24, v22
	v_mul_f32_e32 v29, v28, v27
	v_fma_f32 v30, -v26, v29, v28
	v_fmac_f32_e32 v29, v30, v27
	v_fma_f32 v26, -v26, v29, v28
	v_div_fmas_f32 v26, v26, v27, v29
	v_div_fixup_f32 v24, v26, v24, v22
	v_pk_mul_f32 v[0:1], v[0:1], v[24:25]
	v_lshlrev_b32_e32 v24, 16, v23
	v_cvt_pk_bf16_f32 v0, v0, v1
	v_and_b32_e32 v1, 0xffff0000, v23
	v_mul_f32_e32 v22, 0xbfb8aa3b, v24
	v_mul_f32_e32 v23, 0xbfb8aa3b, v1
	v_exp_f32_e32 v22, v22
	v_exp_f32_e32 v23, v23
	s_nop 0
	v_pk_add_f32 v[22:23], v[22:23], 1.0 op_sel_hi:[1,0]
	s_nop 0
	v_div_scale_f32 v25, s[0:1], v23, v23, v1
	v_rcp_f32_e32 v26, v25
	s_nop 0
	v_fma_f32 v27, -v25, v26, 1.0
	v_fmac_f32_e32 v26, v27, v26
	v_div_scale_f32 v27, vcc, v1, v23, v1
	v_mul_f32_e32 v28, v27, v26
	v_fma_f32 v29, -v25, v28, v27
	v_fmac_f32_e32 v28, v29, v26
	v_fma_f32 v25, -v25, v28, v27
	v_div_fmas_f32 v25, v25, v26, v28
	v_div_fixup_f32 v23, v25, v23, v1
	v_div_scale_f32 v1, s[0:1], v22, v22, v24
	v_rcp_f32_e32 v25, v1
	s_nop 0
	v_fma_f32 v26, -v1, v25, 1.0
	v_fmac_f32_e32 v25, v26, v25
	v_div_scale_f32 v26, vcc, v24, v22, v24
	v_mul_f32_e32 v27, v26, v25
	v_fma_f32 v28, -v1, v27, v26
	v_fmac_f32_e32 v27, v28, v25
	v_fma_f32 v1, -v1, v27, v26
	v_div_fmas_f32 v1, v1, v25, v27
	v_div_fixup_f32 v22, v1, v22, v24
	v_pk_mul_f32 v[2:3], v[2:3], v[22:23]
	s_nop 0
	v_cvt_pk_bf16_f32 v1, v2, v3
	v_lshl_add_u64 v[2:3], v[20:21], 0, v[38:39]
	global_store_dwordx2 v[2:3], v[0:1], off
	s_nop 0
	s_waitcnt lgkmcnt(0)
	v_mov_b32_e32 v0, v214
	v_mov_b32_e32 v1, v215
	v_and_b32_e32 v22, 0xffff0000, v0
	v_lshlrev_b32_e32 v0, 16, v0
	v_mul_f32_e32 v2, 0xbfb8aa3b, v0
	v_mul_f32_e32 v3, 0xbfb8aa3b, v22
	v_exp_f32_e32 v2, v2
	v_exp_f32_e32 v3, v3
	s_nop 0
	v_pk_add_f32 v[2:3], v[2:3], 1.0 op_sel_hi:[1,0]
	s_nop 0
	v_div_scale_f32 v23, s[0:1], v3, v3, v22
	v_rcp_f32_e32 v24, v23
	s_nop 0
	v_fma_f32 v25, -v23, v24, 1.0
	v_fmac_f32_e32 v24, v25, v24
	v_div_scale_f32 v25, vcc, v22, v3, v22
	v_mul_f32_e32 v26, v25, v24
	v_fma_f32 v27, -v23, v26, v25
	v_fmac_f32_e32 v26, v27, v24
	v_fma_f32 v23, -v23, v26, v25
	v_div_fmas_f32 v23, v23, v24, v26
	v_div_fixup_f32 v3, v23, v3, v22
	v_div_scale_f32 v22, s[0:1], v2, v2, v0
	v_rcp_f32_e32 v23, v22
	s_nop 0
	v_fma_f32 v24, -v22, v23, 1.0
	v_fmac_f32_e32 v23, v24, v23
	v_div_scale_f32 v24, vcc, v0, v2, v0
	v_mul_f32_e32 v25, v24, v23
	v_fma_f32 v26, -v22, v25, v24
	v_fmac_f32_e32 v25, v26, v23
	v_fma_f32 v22, -v22, v25, v24
	v_div_fmas_f32 v22, v22, v23, v25
	v_div_fixup_f32 v2, v22, v2, v0
	v_pk_mul_f32 v[2:3], v[4:5], v[2:3]
	v_and_b32_e32 v22, 0xffff0000, v1
	v_lshlrev_b32_e32 v1, 16, v1
	v_cvt_pk_bf16_f32 v0, v2, v3
	v_mul_f32_e32 v2, 0xbfb8aa3b, v1
	v_mul_f32_e32 v3, 0xbfb8aa3b, v22
	v_exp_f32_e32 v2, v2
	v_exp_f32_e32 v3, v3
	v_pk_mul_f32 v[4:5], v[6:7], v[32:33] op_sel_hi:[1,0]
	v_pk_add_f32 v[2:3], v[2:3], 1.0 op_sel_hi:[1,0]
	s_nop 0
	v_div_scale_f32 v6, s[0:1], v3, v3, v22
	v_rcp_f32_e32 v7, v6
	s_nop 0
	v_fma_f32 v23, -v6, v7, 1.0
	v_fmac_f32_e32 v7, v23, v7
	v_div_scale_f32 v23, vcc, v22, v3, v22
	v_mul_f32_e32 v24, v23, v7
	v_fma_f32 v25, -v6, v24, v23
	v_fmac_f32_e32 v24, v25, v7
	v_fma_f32 v6, -v6, v24, v23
	v_div_fmas_f32 v6, v6, v7, v24
	v_div_fixup_f32 v3, v6, v3, v22
	v_div_scale_f32 v6, s[0:1], v2, v2, v1
	v_rcp_f32_e32 v7, v6
	s_nop 0
	v_fma_f32 v22, -v6, v7, 1.0
	v_fmac_f32_e32 v7, v22, v7
	v_div_scale_f32 v22, vcc, v1, v2, v1
	v_mul_f32_e32 v23, v22, v7
	v_fma_f32 v24, -v6, v23, v22
	v_fmac_f32_e32 v23, v24, v7
	v_fma_f32 v6, -v6, v23, v22
	v_div_fmas_f32 v6, v6, v7, v23
	v_div_fixup_f32 v2, v6, v2, v1
	v_pk_mul_f32 v[2:3], v[4:5], v[2:3]
	v_pk_mul_f32 v[4:5], v[8:9], v[32:33] op_sel_hi:[1,0]
	v_cvt_pk_bf16_f32 v1, v2, v3
	v_lshl_add_u64 v[2:3], v[20:21], 0, v[36:37]
	global_store_dwordx2 v[2:3], v[0:1], off
	s_nop 0
	s_waitcnt lgkmcnt(0)
; DI size_t kblk(int row, int col, int nrows) { return ((size_t)(col >> 5) * nrows + row) * 32 + (col & 31); }
; DI float bf2f(bf16_t v) { return __uint_as_float(((unsigned)v) << 16); }
; DI unsigned pk2(float a, float b) { hwf32x2 f = {a, b}; hwbf16x2 r = __builtin_convertvector(f, hwbf16x2); return __builtin_bit_cast(unsigned, r); }
; DI float siluf_(float z) { return z / (1.f + __expf(-z)); }
; template <int MODE>
; DI void attn_mfma(const Params& p, int l, int b, int hd, int qb, unsigned char* smem) {
;     ...
;     const float i0 = 1.f / ltot;
; #pragma unroll
;     for (int vt = 0; vt < 2; ++vt)
; #pragma unroll
;       for (int g4 = 0; g4 < 4; ++g4) {
;         const int v0 = vt * 32 + 8 * g4 + 4 * h2;
;         const ushort4 gt = *(const ushort4*)(P + qrow * PW + GATE + 512 + hd * 64 + v0);
;         uint2 o;
;         o.x = pk2(O[vt][4 * g4 + 0] * i0 * siluf_(bf2f(gt.x)), O[vt][4 * g4 + 1] * i0 * siluf_(bf2f(gt.y)));
;         o.y = pk2(O[vt][4 * g4 + 2] * i0 * siluf_(bf2f(gt.z)), O[vt][4 * g4 + 3] * i0 * siluf_(bf2f(gt.w)));
;         *(uint2*)(MIX + kblk((int)qrow, 512 + hd * 64 + v0, ROWS)) = o;
;       }
	v_mov_b32_e32 v0, v216
	v_mov_b32_e32 v1, v217
	v_and_b32_e32 v6, 0xffff0000, v0
	v_lshlrev_b32_e32 v0, 16, v0
	v_mul_f32_e32 v2, 0xbfb8aa3b, v0
	v_mul_f32_e32 v3, 0xbfb8aa3b, v6
	v_exp_f32_e32 v2, v2
	v_exp_f32_e32 v3, v3
	s_nop 0
	v_pk_add_f32 v[2:3], v[2:3], 1.0 op_sel_hi:[1,0]
	s_nop 0
	v_div_scale_f32 v7, s[0:1], v3, v3, v6
	v_rcp_f32_e32 v8, v7
	s_nop 0
	v_fma_f32 v9, -v7, v8, 1.0
	v_fmac_f32_e32 v8, v9, v8
	v_div_scale_f32 v9, vcc, v6, v3, v6
	v_mul_f32_e32 v22, v9, v8
	v_fma_f32 v23, -v7, v22, v9
	v_fmac_f32_e32 v22, v23, v8
	v_fma_f32 v7, -v7, v22, v9
	v_div_fmas_f32 v7, v7, v8, v22
	v_div_fixup_f32 v3, v7, v3, v6
	v_div_scale_f32 v6, s[0:1], v2, v2, v0
	v_rcp_f32_e32 v7, v6
	s_nop 0
	v_fma_f32 v8, -v6, v7, 1.0
	v_fmac_f32_e32 v7, v8, v7
	v_div_scale_f32 v8, vcc, v0, v2, v0
	v_mul_f32_e32 v9, v8, v7
	v_fma_f32 v22, -v6, v9, v8
	v_fmac_f32_e32 v9, v22, v7
	v_fma_f32 v6, -v6, v9, v8
	v_div_fmas_f32 v6, v6, v7, v9
	v_div_fixup_f32 v2, v6, v2, v0
	v_pk_mul_f32 v[2:3], v[4:5], v[2:3]
	v_and_b32_e32 v6, 0xffff0000, v1
	v_lshlrev_b32_e32 v1, 16, v1
	v_cvt_pk_bf16_f32 v0, v2, v3
	v_mul_f32_e32 v2, 0xbfb8aa3b, v1
	v_mul_f32_e32 v3, 0xbfb8aa3b, v6
	v_exp_f32_e32 v2, v2
	v_exp_f32_e32 v3, v3
	v_pk_mul_f32 v[4:5], v[10:11], v[32:33] op_sel_hi:[1,0]
	v_pk_add_f32 v[2:3], v[2:3], 1.0 op_sel_hi:[1,0]
	s_nop 0
	v_div_scale_f32 v7, s[0:1], v3, v3, v6
	v_rcp_f32_e32 v8, v7
	s_nop 0
	v_fma_f32 v9, -v7, v8, 1.0
	v_fmac_f32_e32 v8, v9, v8
	v_div_scale_f32 v9, vcc, v6, v3, v6
	v_mul_f32_e32 v10, v9, v8
	v_fma_f32 v11, -v7, v10, v9
	v_fmac_f32_e32 v10, v11, v8
	v_fma_f32 v7, -v7, v10, v9
	v_div_fmas_f32 v7, v7, v8, v10
	v_div_fixup_f32 v3, v7, v3, v6
	v_div_scale_f32 v6, s[0:1], v2, v2, v1
	v_rcp_f32_e32 v7, v6
	s_nop 0
	v_fma_f32 v8, -v6, v7, 1.0
	v_fmac_f32_e32 v7, v8, v7
	v_div_scale_f32 v8, vcc, v1, v2, v1
	v_mul_f32_e32 v9, v8, v7
	v_fma_f32 v10, -v6, v9, v8
	v_fmac_f32_e32 v9, v10, v7
	v_fma_f32 v6, -v6, v9, v8
	v_div_fmas_f32 v6, v6, v7, v9
	v_div_fixup_f32 v2, v6, v2, v1
	v_pk_mul_f32 v[2:3], v[4:5], v[2:3]
	v_pk_mul_f32 v[4:5], v[12:13], v[32:33] op_sel_hi:[1,0]
	v_cvt_pk_bf16_f32 v1, v2, v3
	v_lshl_add_u64 v[2:3], v[20:21], 0, v[18:19]
	global_store_dwordx2 v[2:3], v[0:1], off
	s_nop 0
	s_waitcnt lgkmcnt(0)
	v_mov_b32_e32 v0, v218
	v_mov_b32_e32 v1, v219
	v_and_b32_e32 v6, 0xffff0000, v0
	v_lshlrev_b32_e32 v0, 16, v0
	v_mul_f32_e32 v2, 0xbfb8aa3b, v0
	v_mul_f32_e32 v3, 0xbfb8aa3b, v6
	v_exp_f32_e32 v2, v2
	v_exp_f32_e32 v3, v3
	s_nop 0
	v_pk_add_f32 v[2:3], v[2:3], 1.0 op_sel_hi:[1,0]
	s_nop 0
	v_div_scale_f32 v7, s[0:1], v3, v3, v6
	v_rcp_f32_e32 v8, v7
	s_nop 0
	v_fma_f32 v9, -v7, v8, 1.0
	v_fmac_f32_e32 v8, v9, v8
	v_div_scale_f32 v9, vcc, v6, v3, v6
	v_mul_f32_e32 v10, v9, v8
	v_fma_f32 v11, -v7, v10, v9
	v_fmac_f32_e32 v10, v11, v8
	v_fma_f32 v7, -v7, v10, v9
	v_div_fmas_f32 v7, v7, v8, v10
	v_div_fixup_f32 v3, v7, v3, v6
	v_div_scale_f32 v6, s[0:1], v2, v2, v0
	v_rcp_f32_e32 v7, v6
	s_nop 0
	v_fma_f32 v8, -v6, v7, 1.0
	v_fmac_f32_e32 v7, v8, v7
	v_div_scale_f32 v8, vcc, v0, v2, v0
	v_mul_f32_e32 v9, v8, v7
	v_fma_f32 v10, -v6, v9, v8
	v_fmac_f32_e32 v9, v10, v7
	v_fma_f32 v6, -v6, v9, v8
	v_div_fmas_f32 v6, v6, v7, v9
	v_div_fixup_f32 v2, v6, v2, v0
	v_pk_mul_f32 v[2:3], v[4:5], v[2:3]
	v_and_b32_e32 v6, 0xffff0000, v1
	v_lshlrev_b32_e32 v1, 16, v1
	v_cvt_pk_bf16_f32 v0, v2, v3
	v_mul_f32_e32 v2, 0xbfb8aa3b, v1
	v_mul_f32_e32 v3, 0xbfb8aa3b, v6
	v_exp_f32_e32 v2, v2
	v_exp_f32_e32 v3, v3
	v_pk_mul_f32 v[4:5], v[14:15], v[32:33] op_sel_hi:[1,0]
	v_pk_add_f32 v[2:3], v[2:3], 1.0 op_sel_hi:[1,0]
	s_nop 0
	v_div_scale_f32 v7, s[0:1], v3, v3, v6
	v_rcp_f32_e32 v8, v7
	s_nop 0
	v_fma_f32 v9, -v7, v8, 1.0
	v_fmac_f32_e32 v8, v9, v8
	v_div_scale_f32 v9, vcc, v6, v3, v6
	v_mul_f32_e32 v10, v9, v8
	v_fma_f32 v11, -v7, v10, v9
	v_fmac_f32_e32 v10, v11, v8
	v_fma_f32 v7, -v7, v10, v9
	v_div_fmas_f32 v7, v7, v8, v10
	v_div_fixup_f32 v3, v7, v3, v6
	v_div_scale_f32 v6, s[0:1], v2, v2, v1
	v_rcp_f32_e32 v7, v6
	s_nop 0
	v_fma_f32 v8, -v6, v7, 1.0
	v_fmac_f32_e32 v7, v8, v7
	v_div_scale_f32 v8, vcc, v1, v2, v1
	v_mul_f32_e32 v9, v8, v7
	v_fma_f32 v10, -v6, v9, v8
	v_fmac_f32_e32 v9, v10, v7
	v_fma_f32 v6, -v6, v9, v8
	v_div_fmas_f32 v6, v6, v7, v9
	v_div_fixup_f32 v2, v6, v2, v1
	v_pk_mul_f32 v[2:3], v[4:5], v[2:3]
	s_nop 0
	v_cvt_pk_bf16_f32 v1, v2, v3
	v_lshl_add_u64 v[2:3], v[20:21], 0, v[16:17]
	global_store_dwordx2 v[2:3], v[0:1], off

; template <int MX>
; DI RecRaw rec_load(const Params& p, int b, int h, int dir, int T0, int tid) {
;   const bf16_t* P = (const bf16_t*)(p.ws + WS_P);
;   const int tt = tid >> 2, k0 = (tid & 3) * 16;
;   const size_t row = (size_t)b * NTOK + T0 + tt;
;   const bf16_t* rp = P + row * PW;
;   RecRaw w;
;   if (MX == 0) {
;     const int fcol = (dir ? B_FB : B_FF) + h * 64 + k0;
;     w.a0 = *(const uint4*)(rp + fcol); w.a1 = *(const uint4*)(rp + fcol + 8);
;     w.b0 = *(const uint4*)(rp + B_Q + h * 64 + k0); w.b1 = *(const uint4*)(rp + B_Q + h * 64 + k0 + 8);
;     w.c0 = *(const uint4*)(rp + B_I + h * 64 + k0); w.c1 = *(const uint4*)(rp + B_I + h * 64 + k0 + 8);
;     w.ig = 0.f; w.fg = 0.f;
;   } else {
;     w.a0 = *(const uint4*)(rp + D_K + h * 64 + k0); w.a1 = *(const uint4*)(rp + D_K + h * 64 + k0 + 8);
;     w.b0 = *(const uint4*)(rp + D_Q + h * 64 + k0); w.b1 = *(const uint4*)(rp + D_Q + h * 64 + k0 + 8);
;     w.c0 = *(const uint4*)(rp + D_V + h * 64 + k0); w.c1 = *(const uint4*)(rp + D_V + h * 64 + k0 + 8);
;     const float* G = (const float*)(p.ws + WS_GATES) + row * 16;
;     w.ig = G[dir * 4 + h]; w.fg = G[8 + dir * 4 + h];
;   }
;   return w;
; }
; template <int MX>
; DI void rec_output(const Params& p, int l, int b, int h, int sc, unsigned char* smem) {
;     ...
; #pragma unroll 1
;     for (int ci = 0; ci < 4; ++ci) {
;       const int c = dir == 0 ? ci : 3 - ci;
;       const int cn = dir == 0 ? (ci < 3 ? ci + 1 : ci) : (ci < 3 ? 2 - ci : 0);
;       const RecRaw nxt = rec_load<MX>(p, b, h, dir, sc * 256 + cn * 64, tid);
;       rec_chunk<MX, true>(p, l, b, h, dir, sc * 256 + c * 64, smem, St, nst, dtot, tid, raw);
;       raw = nxt;
;     }
.LBB0_845:
	s_or_b64 exec, exec, s[0:1]
	s_add_i32 s55, s55, -1
	s_add_i32 s54, s54, 1
	s_cmp_eq_u32 s55, -2
	s_waitcnt vmcnt(0)
	v_mov_b32_e32 v64, v237
	v_mov_b32_e32 v65, v238
	v_mov_b64_e32 v[56:57], v[36:37]
	v_mov_b64_e32 v[58:59], v[38:39]
	v_mov_b64_e32 v[48:49], v[20:21]
	v_mov_b64_e32 v[50:51], v[22:23]
	v_mov_b64_e32 v[40:41], v[16:17]
	v_mov_b64_e32 v[42:43], v[18:19]
	v_mov_b64_e32 v[44:45], v[32:33]
	v_mov_b64_e32 v[46:47], v[34:35]
	v_mov_b64_e32 v[60:61], v[24:25]
	v_mov_b64_e32 v[62:63], v[26:27]
	v_mov_b64_e32 v[52:53], v[28:29]
	v_mov_b64_e32 v[54:55], v[30:31]
	s_cbranch_scc1 .LBB0_834
.LBB0_846:
	v_add_co_u32_e64 v93, s[0:1], s55, 1
	s_and_b64 s[0:1], s[0:1], exec
	s_cselect_b32 s21, 3, s54
	s_cselect_b32 s44, 0, s55
	s_and_b64 s[0:1], s[40:41], exec
	s_cselect_b32 s0, s21, s44
	s_lshl_b32 s0, s0, 6
	s_add_i32 s0, s0, s50
	s_ashr_i32 s1, s0, 31
	v_lshl_add_u64 v[66:67], v[82:83], 0, s[0:1]
	v_mov_b64_e32 v[16:17], s[24:25]
	v_mad_u64_u32 v[16:17], s[0:1], v66, s33, v[16:17]
	v_mad_i32_i24 v17, v67, s33, v17
	v_lshl_add_u64 v[16:17], v[16:17], 0, s[26:27]
	v_lshl_add_u64 v[24:25], v[16:17], 0, v[98:99]
	s_mov_b64 s[0:1], 0x1400
	v_lshl_add_u64 v[16:17], v[24:25], 0, s[0:1]
	s_mov_b64 s[0:1], 0x1200
	v_add_co_u32_e32 v26, vcc, s16, v24
	v_lshl_add_u64 v[28:29], v[24:25], 0, s[0:1]
	s_mov_b64 s[0:1], 0x1600
	v_addc_co_u32_e32 v27, vcc, 0, v25, vcc
	v_lshl_add_u64 v[30:31], v[24:25], 0, s[0:1]
	global_load_dwordx4 v[20:23], v[16:17], off offset:16
	s_nop 0
	global_load_dwordx4 v[16:19], v[26:27], off offset:512
	global_load_dwordx4 v[36:39], v[26:27], off offset:1024
	s_nop 0
	global_load_dwordx4 v[24:27], v[26:27], off offset:1536
	s_nop 0
	global_load_dwordx4 v[32:35], v[28:29], off offset:16
	s_nop 0
	global_load_dwordx4 v[28:31], v[30:31], off offset:16
	v_lshlrev_b64 v[66:67], 6, v[66:67]
	v_lshl_add_u64 v[66:67], s[34:35], 0, v[66:67]
	global_load_dword v237, v[66:67], off
	global_load_dword v238, v[66:67], off offset:32
	s_mov_b32 s0, 0xc1a00000
	s_waitcnt vmcnt(8) lgkmcnt(0)
	v_cmp_ngt_f32_e32 vcc, s0, v65
	s_and_saveexec_b64 s[0:1], vcc
	s_xor_b64 s[0:1], exec, s[0:1]
	s_cbranch_execz .LBB0_936
	v_mul_f32_e32 v65, 0xbfb8aa3b, v65
	v_exp_f32_e32 v65, v65
	s_nop 0
	v_add_f32_e32 v65, 1.0, v65
	v_log_f32_e32 v65, v65
	s_nop 0
	v_xor_b32_e32 v66, 0x80000000, v65
	s_andn2_saveexec_b64 s[0:1], s[0:1]
	s_cbranch_execnz .LBB0_937
